# s5_y and glu 128x128 GEMM K-loops fully unrolled with 4-tile-deep register prefetch (SGPR row bases + immediate K offsets); glu epilogue loop software-pipelined
# speedup vs baseline: 1.0315x; 1.0131x over previous
.LBB0_700:
	s_and_b32 s0, s12, 0xff
	s_mulk_i32 s0, 0xab
	s_lshr_b32 s0, s0, 11
	v_readlane_b32 s1, v255, 16
	s_add_i32 s2, s1, s0
	s_mul_i32 s0, s0, 12
	s_sub_i32 s3, s12, s0
	s_lshl_b32 s1, s3, 7
	s_lshl_b32 s0, s2, 9
	s_and_b32 s38, s1, 0x180
	s_or_b32 s0, s0, s38
	s_mulk_i32 s0, 0x600
	s_add_u32 s0, s70, s0
	s_addc_u32 s1, s71, 0
	s_mov_b64 s[22:23], s[0:1]
	s_lshl_b32 s3, s3, 5
	s_mul_i32 s10, s2, 0x180
	s_and_b32 s39, s3, 0x180
	s_add_i32 s10, s10, s39
	v_mov_b32_e32 v46, v235
	s_lshl_b32 s3, s10, 10
	s_add_u32 s40, s68, s3
	v_ashrrev_i32_e32 v32, 3, v46
	v_ashrrev_i32_e32 v33, 31, v32
	s_addc_u32 s41, s69, 0
	s_mov_b64 s[14:15], s[40:41]
	v_lshlrev_b64 v[0:1], 10, v[32:33]
	v_lshlrev_b32_e32 v47, 4, v46
	v_lshl_add_u64 v[0:1], s[40:41], 0, v[0:1]
	v_and_b32_e32 v192, 0x70, v47
	v_lshlrev_b32_e32 v230, 10, v32
	v_or_b32_e32 v230, v230, v192
	v_mul_u32_u24_e32 v231, 0x600, v32
	v_add_u32_e32 v231, v231, v192
	v_lshlrev_b32_e32 v232, 9, v32
	v_or_b32_e32 v232, v232, v192
	v_lshl_add_u64 v[128:129], v[0:1], 0, v[192:193]
	v_mov_b64_e32 v[0:1], s[0:1]
	v_mad_i64_i32 v[0:1], s[0:1], v32, s78, v[0:1]
	v_add_co_u32_e32 v34, vcc, s88, v128
	v_lshl_add_u64 v[130:131], v[0:1], 0, v[192:193]
	s_nop 0
	v_addc_co_u32_e32 v35, vcc, 0, v129, vcc
	v_add_co_u32_e32 v36, vcc, s8, v130
	v_addc_co_u32_e32 v37, vcc, 0, v131, vcc
	v_add_co_u32_e32 v38, vcc, s97, v128
	s_nop 0
	v_addc_co_u32_e32 v39, vcc, 0, v129, vcc
	v_add_co_u32_e32 v40, vcc, s76, v130
	s_nop 0
	v_addc_co_u32_e32 v41, vcc, 0, v131, vcc
	v_add_co_u32_e32 v42, vcc, s9, v130
	s_nop 0
	v_addc_co_u32_e32 v43, vcc, 0, v131, vcc
	v_add_co_u32_e32 v44, vcc, s76, v128
	s_nop 0
	v_addc_co_u32_e32 v45, vcc, 0, v129, vcc
	v_and_b32_e32 v48, 31, v46
	v_lshrrev_b32_e32 v51, 1, v46
	s_mov_b32 s0, 0x1ffffc0
	v_lshrrev_b32_e32 v49, 5, v46
	v_bfe_u32 v50, v46, 5, 1
	v_bfe_u32 v52, v46, 1, 3
	v_lshlrev_b32_e32 v53, 7, v46
	v_lshlrev_b32_e32 v54, 7, v32
	v_xor_b32_e32 v46, v47, v46
	v_and_or_b32 v47, v51, s0, v48
	s_movk_i32 s0, 0x70
	v_and_or_b32 v46, v46, s0, v54
	v_add_u32_e32 v134, s13, v46
	v_readlane_b32 s44, v253, 8
	s_lshl_b32 s0, s10, 9
	v_readlane_b32 s46, v253, 10
	v_readlane_b32 s47, v253, 11
	s_add_u32 s0, s46, s0
	v_lshlrev_b64 v[32:33], 9, v[32:33]
	s_addc_u32 s1, s47, 0
	s_mov_b64 s[80:81], s[0:1]
	v_and_b32_e32 v48, 0x2f80, v53
	v_lshl_add_u64 v[32:33], s[0:1], 0, v[32:33]
	s_mov_b32 s3, 0
	v_lshl_add_u64 v[132:133], v[32:33], 0, v[192:193]
	v_lshl_add_u32 v135, v47, 7, s13
	v_add_u32_e32 v136, s13, v48
	v_readlane_b32 s45, v253, 9
	v_readlane_b32 s48, v253, 12
	v_readlane_b32 s49, v253, 13
	v_readlane_b32 s50, v253, 14
	v_readlane_b32 s51, v253, 15
	v_bitop3_b32 v0, v49, v52, 1 bitop3:0x6c
	v_lshlrev_b32_e32 v137, 4, v0
	v_bitop3_b32 v0, v50, v52, 2 bitop3:0x36
	v_lshlrev_b32_e32 v138, 4, v0
	v_bitop3_b32 v0, v50, v52, 4 bitop3:0x36
	v_lshlrev_b32_e32 v139, 4, v0
	v_bitop3_b32 v0, v50, v52, 6 bitop3:0x36
	v_lshlrev_b32_e32 v140, 4, v0
	s_add_u32 s16, s14, 0x8000
	s_addc_u32 s17, s15, 0
	s_add_u32 s18, s14, 0x10000
	s_addc_u32 s19, s15, 0
	s_add_u32 s20, s14, 0x18000
	s_addc_u32 s21, s15, 0
	s_add_u32 s54, s22, 0xc000
	s_addc_u32 s55, s23, 0
	s_add_u32 s72, s22, 0x18000
	s_addc_u32 s73, s23, 0
	s_add_u32 s74, s22, 0x24000
	s_addc_u32 s75, s23, 0
	s_add_u32 s86, s80, 0x4000
	s_addc_u32 s87, s81, 0
	s_add_u32 s40, s80, 0x8000
	s_addc_u32 s41, s81, 0
	s_add_u32 s44, s80, 0xc000
	s_addc_u32 s45, s81, 0
	global_load_dwordx4 v[64:67], v230, s[14:15]
	global_load_dwordx4 v[68:71], v230, s[16:17]
	global_load_dwordx4 v[72:75], v230, s[18:19]
	global_load_dwordx4 v[76:79], v230, s[20:21]
	global_load_dwordx4 v[80:83], v231, s[22:23]
	global_load_dwordx4 v[84:87], v231, s[54:55]
	global_load_dwordx4 v[88:91], v231, s[72:73]
	global_load_dwordx4 v[92:95], v231, s[74:75]
	global_load_dwordx4 v[96:99], v230, s[14:15] offset:128
	global_load_dwordx4 v[100:103], v230, s[16:17] offset:128
	global_load_dwordx4 v[104:107], v230, s[18:19] offset:128
	global_load_dwordx4 v[108:111], v230, s[20:21] offset:128
	global_load_dwordx4 v[112:115], v231, s[22:23] offset:128
	global_load_dwordx4 v[116:119], v231, s[54:55] offset:128
	global_load_dwordx4 v[120:123], v231, s[72:73] offset:128
	global_load_dwordx4 v[124:127], v231, s[74:75] offset:128
	global_load_dwordx4 v[160:163], v230, s[14:15] offset:256
	global_load_dwordx4 v[164:167], v230, s[16:17] offset:256
	global_load_dwordx4 v[168:171], v230, s[18:19] offset:256
	global_load_dwordx4 v[172:175], v230, s[20:21] offset:256
	global_load_dwordx4 v[176:179], v231, s[22:23] offset:256
	global_load_dwordx4 v[180:183], v231, s[54:55] offset:256
	global_load_dwordx4 v[184:187], v231, s[72:73] offset:256
	global_load_dwordx4 v[188:191], v231, s[74:75] offset:256
	global_load_dwordx4 v[196:199], v230, s[14:15] offset:384
	global_load_dwordx4 v[200:203], v230, s[16:17] offset:384
	global_load_dwordx4 v[204:207], v230, s[18:19] offset:384
	global_load_dwordx4 v[208:211], v230, s[20:21] offset:384
	global_load_dwordx4 v[212:215], v231, s[22:23] offset:384
	global_load_dwordx4 v[216:219], v231, s[54:55] offset:384
	global_load_dwordx4 v[220:223], v231, s[72:73] offset:384
	global_load_dwordx4 v[224:227], v231, s[74:75] offset:384
	v_add_u32_e32 v128, v135, v137
	v_add_u32_e32 v132, v136, v137
	v_add_u32_e32 v129, v135, v138
	v_add_u32_e32 v133, v136, v138
	v_add_u32_e32 v130, v135, v139
	v_add_u32_e32 v228, v136, v139
	v_add_u32_e32 v131, v135, v140
	v_add_u32_e32 v229, v136, v140
	v_mov_b32_e32 v0, 0
	v_mov_b32_e32 v1, v0
	v_mov_b32_e32 v2, v0
	v_mov_b32_e32 v3, v0
	v_mov_b32_e32 v4, v0
	v_mov_b32_e32 v5, v0
	v_mov_b32_e32 v6, v0
	v_mov_b32_e32 v7, v0
	v_mov_b32_e32 v8, v0
	v_mov_b32_e32 v9, v0
	v_mov_b32_e32 v10, v0
	v_mov_b32_e32 v11, v0
	v_mov_b32_e32 v12, v0
	v_mov_b32_e32 v13, v0
	v_mov_b32_e32 v14, v0
	v_mov_b32_e32 v15, v0
	v_mov_b32_e32 v16, v0
	v_mov_b32_e32 v17, v0
	v_mov_b32_e32 v18, v0
	v_mov_b32_e32 v19, v0
	v_mov_b32_e32 v20, v0
	v_mov_b32_e32 v21, v0
	v_mov_b32_e32 v22, v0
	v_mov_b32_e32 v23, v0
	v_mov_b32_e32 v24, v0
	v_mov_b32_e32 v25, v0
	v_mov_b32_e32 v26, v0
	v_mov_b32_e32 v27, v0
	v_mov_b32_e32 v28, v0
	v_mov_b32_e32 v29, v0
	v_mov_b32_e32 v30, v0
	v_mov_b32_e32 v31, v0
	v_mov_b32_e32 v32, v0
	v_mov_b32_e32 v33, v0
	v_mov_b32_e32 v34, v0
	v_mov_b32_e32 v35, v0
	v_mov_b32_e32 v36, v0
	v_mov_b32_e32 v37, v0
	v_mov_b32_e32 v38, v0
	v_mov_b32_e32 v39, v0
	v_mov_b32_e32 v40, v0
	v_mov_b32_e32 v41, v0
	v_mov_b32_e32 v42, v0
	v_mov_b32_e32 v43, v0
	v_mov_b32_e32 v44, v0
	v_mov_b32_e32 v45, v0
	v_mov_b32_e32 v46, v0
	v_mov_b32_e32 v47, v0
	v_mov_b32_e32 v48, v0
	v_mov_b32_e32 v49, v0
	v_mov_b32_e32 v50, v0
	v_mov_b32_e32 v51, v0
	v_mov_b32_e32 v52, v0
	v_mov_b32_e32 v53, v0
	v_mov_b32_e32 v54, v0
	v_mov_b32_e32 v55, v0
	v_mov_b32_e32 v56, v0
	v_mov_b32_e32 v57, v0
	v_mov_b32_e32 v58, v0
	v_mov_b32_e32 v59, v0
	v_mov_b32_e32 v60, v0
	v_mov_b32_e32 v61, v0
	v_mov_b32_e32 v62, v0
	v_mov_b32_e32 v63, v0
	s_waitcnt vmcnt(24)
	ds_write_b128 v134, v[64:67]
	ds_write_b128 v134, v[80:83] offset:16384
	ds_write_b128 v134, v[68:71] offset:4096
	ds_write_b128 v134, v[84:87] offset:20480
	ds_write_b128 v134, v[72:75] offset:8192
	ds_write_b128 v134, v[88:91] offset:24576
	ds_write_b128 v134, v[76:79] offset:12288
	ds_write_b128 v134, v[92:95] offset:28672
	s_waitcnt lgkmcnt(0)
	s_barrier
	global_load_dwordx4 v[64:67], v230, s[14:15] offset:512
	global_load_dwordx4 v[68:71], v230, s[16:17] offset:512
	global_load_dwordx4 v[72:75], v230, s[18:19] offset:512
	global_load_dwordx4 v[76:79], v230, s[20:21] offset:512
	global_load_dwordx4 v[80:83], v231, s[22:23] offset:512
	global_load_dwordx4 v[84:87], v231, s[54:55] offset:512
	global_load_dwordx4 v[88:91], v231, s[72:73] offset:512
	global_load_dwordx4 v[92:95], v231, s[74:75] offset:512
	ds_read_b128 v[142:145], v128
	ds_read_b128 v[146:149], v132 offset:16384
	ds_read_b128 v[150:153], v132 offset:20480
	s_waitcnt lgkmcnt(1)
	v_mfma_f32_32x32x16_bf16 v[48:63], v[142:145], v[146:149], v[48:63]
	s_waitcnt lgkmcnt(0)
	v_mfma_f32_32x32x16_bf16 v[32:47], v[142:145], v[150:153], v[32:47]
	ds_read_b128 v[142:145], v128 offset:4096
	s_waitcnt lgkmcnt(0)
	v_mfma_f32_32x32x16_bf16 v[16:31], v[142:145], v[146:149], v[16:31]
	ds_read_b128 v[146:149], v133 offset:16384
	v_mfma_f32_32x32x16_bf16 v[0:15], v[142:145], v[150:153], v[0:15]
	ds_read_b128 v[142:145], v129
	ds_read_b128 v[150:153], v133 offset:20480
	s_waitcnt lgkmcnt(1)
	v_mfma_f32_32x32x16_bf16 v[48:63], v[142:145], v[146:149], v[48:63]
	s_waitcnt lgkmcnt(0)
	v_mfma_f32_32x32x16_bf16 v[32:47], v[142:145], v[150:153], v[32:47]
	ds_read_b128 v[142:145], v129 offset:4096
	s_waitcnt lgkmcnt(0)
	v_mfma_f32_32x32x16_bf16 v[16:31], v[142:145], v[146:149], v[16:31]
	ds_read_b128 v[146:149], v228 offset:16384
	v_mfma_f32_32x32x16_bf16 v[0:15], v[142:145], v[150:153], v[0:15]
	ds_read_b128 v[142:145], v130
	ds_read_b128 v[150:153], v228 offset:20480
	s_waitcnt lgkmcnt(1)
	v_mfma_f32_32x32x16_bf16 v[48:63], v[142:145], v[146:149], v[48:63]
	s_waitcnt lgkmcnt(0)
	v_mfma_f32_32x32x16_bf16 v[32:47], v[142:145], v[150:153], v[32:47]
	ds_read_b128 v[142:145], v130 offset:4096
	s_waitcnt lgkmcnt(0)
	v_mfma_f32_32x32x16_bf16 v[16:31], v[142:145], v[146:149], v[16:31]
	ds_read_b128 v[146:149], v229 offset:16384
	v_mfma_f32_32x32x16_bf16 v[0:15], v[142:145], v[150:153], v[0:15]
	ds_read_b128 v[142:145], v131
	ds_read_b128 v[150:153], v229 offset:20480
	s_waitcnt lgkmcnt(1)
	v_mfma_f32_32x32x16_bf16 v[48:63], v[142:145], v[146:149], v[48:63]
	s_waitcnt lgkmcnt(0)
	v_mfma_f32_32x32x16_bf16 v[32:47], v[142:145], v[150:153], v[32:47]
	ds_read_b128 v[142:145], v131 offset:4096
	s_waitcnt lgkmcnt(0)
	v_mfma_f32_32x32x16_bf16 v[16:31], v[142:145], v[146:149], v[16:31]
	v_mfma_f32_32x32x16_bf16 v[0:15], v[142:145], v[150:153], v[0:15]
	s_waitcnt vmcnt(24)
	ds_write_b128 v134, v[96:99] offset:32768
	ds_write_b128 v134, v[112:115] offset:49152
	ds_write_b128 v134, v[100:103] offset:36864
	ds_write_b128 v134, v[116:119] offset:53248
	ds_write_b128 v134, v[104:107] offset:40960
	ds_write_b128 v134, v[120:123] offset:57344
	ds_write_b128 v134, v[108:111] offset:45056
	ds_write_b128 v134, v[124:127] offset:61440
	s_waitcnt lgkmcnt(0)
	s_barrier
	global_load_dwordx4 v[96:99], v230, s[14:15] offset:640
	global_load_dwordx4 v[100:103], v230, s[16:17] offset:640
	global_load_dwordx4 v[104:107], v230, s[18:19] offset:640
	global_load_dwordx4 v[108:111], v230, s[20:21] offset:640
	global_load_dwordx4 v[112:115], v231, s[22:23] offset:640
	global_load_dwordx4 v[116:119], v231, s[54:55] offset:640
	global_load_dwordx4 v[120:123], v231, s[72:73] offset:640
	global_load_dwordx4 v[124:127], v231, s[74:75] offset:640
	ds_read_b128 v[142:145], v128 offset:32768
	ds_read_b128 v[146:149], v132 offset:49152
	ds_read_b128 v[150:153], v132 offset:53248
	s_waitcnt lgkmcnt(1)
	v_mfma_f32_32x32x16_bf16 v[48:63], v[142:145], v[146:149], v[48:63]
	s_waitcnt lgkmcnt(0)
	v_mfma_f32_32x32x16_bf16 v[32:47], v[142:145], v[150:153], v[32:47]
	ds_read_b128 v[142:145], v128 offset:36864
	s_waitcnt lgkmcnt(0)
	v_mfma_f32_32x32x16_bf16 v[16:31], v[142:145], v[146:149], v[16:31]
	ds_read_b128 v[146:149], v133 offset:49152
	v_mfma_f32_32x32x16_bf16 v[0:15], v[142:145], v[150:153], v[0:15]
	ds_read_b128 v[142:145], v129 offset:32768
	ds_read_b128 v[150:153], v133 offset:53248
	s_waitcnt lgkmcnt(1)
	v_mfma_f32_32x32x16_bf16 v[48:63], v[142:145], v[146:149], v[48:63]
	s_waitcnt lgkmcnt(0)
	v_mfma_f32_32x32x16_bf16 v[32:47], v[142:145], v[150:153], v[32:47]
	ds_read_b128 v[142:145], v129 offset:36864
	s_waitcnt lgkmcnt(0)
	v_mfma_f32_32x32x16_bf16 v[16:31], v[142:145], v[146:149], v[16:31]
	ds_read_b128 v[146:149], v228 offset:49152
	v_mfma_f32_32x32x16_bf16 v[0:15], v[142:145], v[150:153], v[0:15]
	ds_read_b128 v[142:145], v130 offset:32768
	ds_read_b128 v[150:153], v228 offset:53248
	s_waitcnt lgkmcnt(1)
	v_mfma_f32_32x32x16_bf16 v[48:63], v[142:145], v[146:149], v[48:63]
	s_waitcnt lgkmcnt(0)
	v_mfma_f32_32x32x16_bf16 v[32:47], v[142:145], v[150:153], v[32:47]
	ds_read_b128 v[142:145], v130 offset:36864
	s_waitcnt lgkmcnt(0)
	v_mfma_f32_32x32x16_bf16 v[16:31], v[142:145], v[146:149], v[16:31]
	ds_read_b128 v[146:149], v229 offset:49152
	v_mfma_f32_32x32x16_bf16 v[0:15], v[142:145], v[150:153], v[0:15]
	ds_read_b128 v[142:145], v131 offset:32768
	ds_read_b128 v[150:153], v229 offset:53248
	s_waitcnt lgkmcnt(1)
	v_mfma_f32_32x32x16_bf16 v[48:63], v[142:145], v[146:149], v[48:63]
	s_waitcnt lgkmcnt(0)
	v_mfma_f32_32x32x16_bf16 v[32:47], v[142:145], v[150:153], v[32:47]
	ds_read_b128 v[142:145], v131 offset:36864
	s_waitcnt lgkmcnt(0)
	v_mfma_f32_32x32x16_bf16 v[16:31], v[142:145], v[146:149], v[16:31]
	v_mfma_f32_32x32x16_bf16 v[0:15], v[142:145], v[150:153], v[0:15]
	s_waitcnt vmcnt(24)
	ds_write_b128 v134, v[160:163]
	ds_write_b128 v134, v[176:179] offset:16384
	ds_write_b128 v134, v[164:167] offset:4096
	ds_write_b128 v134, v[180:183] offset:20480
	ds_write_b128 v134, v[168:171] offset:8192
	ds_write_b128 v134, v[184:187] offset:24576
	ds_write_b128 v134, v[172:175] offset:12288
	ds_write_b128 v134, v[188:191] offset:28672
	s_waitcnt lgkmcnt(0)
	s_barrier
	global_load_dwordx4 v[160:163], v230, s[14:15] offset:768
	global_load_dwordx4 v[164:167], v230, s[16:17] offset:768
	global_load_dwordx4 v[168:171], v230, s[18:19] offset:768
	global_load_dwordx4 v[172:175], v230, s[20:21] offset:768
	global_load_dwordx4 v[176:179], v231, s[22:23] offset:768
	global_load_dwordx4 v[180:183], v231, s[54:55] offset:768
	global_load_dwordx4 v[184:187], v231, s[72:73] offset:768
	global_load_dwordx4 v[188:191], v231, s[74:75] offset:768
	ds_read_b128 v[142:145], v128
	ds_read_b128 v[146:149], v132 offset:16384
	ds_read_b128 v[150:153], v132 offset:20480
	s_waitcnt lgkmcnt(1)
	v_mfma_f32_32x32x16_bf16 v[48:63], v[142:145], v[146:149], v[48:63]
	s_waitcnt lgkmcnt(0)
	v_mfma_f32_32x32x16_bf16 v[32:47], v[142:145], v[150:153], v[32:47]
	ds_read_b128 v[142:145], v128 offset:4096
	s_waitcnt lgkmcnt(0)
	v_mfma_f32_32x32x16_bf16 v[16:31], v[142:145], v[146:149], v[16:31]
	ds_read_b128 v[146:149], v133 offset:16384
	v_mfma_f32_32x32x16_bf16 v[0:15], v[142:145], v[150:153], v[0:15]
	ds_read_b128 v[142:145], v129
	ds_read_b128 v[150:153], v133 offset:20480
	s_waitcnt lgkmcnt(1)
	v_mfma_f32_32x32x16_bf16 v[48:63], v[142:145], v[146:149], v[48:63]
	s_waitcnt lgkmcnt(0)
	v_mfma_f32_32x32x16_bf16 v[32:47], v[142:145], v[150:153], v[32:47]
	ds_read_b128 v[142:145], v129 offset:4096
	s_waitcnt lgkmcnt(0)
	v_mfma_f32_32x32x16_bf16 v[16:31], v[142:145], v[146:149], v[16:31]
	ds_read_b128 v[146:149], v228 offset:16384
	v_mfma_f32_32x32x16_bf16 v[0:15], v[142:145], v[150:153], v[0:15]
	ds_read_b128 v[142:145], v130
	ds_read_b128 v[150:153], v228 offset:20480
	s_waitcnt lgkmcnt(1)
	v_mfma_f32_32x32x16_bf16 v[48:63], v[142:145], v[146:149], v[48:63]
	s_waitcnt lgkmcnt(0)
	v_mfma_f32_32x32x16_bf16 v[32:47], v[142:145], v[150:153], v[32:47]
	ds_read_b128 v[142:145], v130 offset:4096
	s_waitcnt lgkmcnt(0)
	v_mfma_f32_32x32x16_bf16 v[16:31], v[142:145], v[146:149], v[16:31]
	ds_read_b128 v[146:149], v229 offset:16384
	v_mfma_f32_32x32x16_bf16 v[0:15], v[142:145], v[150:153], v[0:15]
	ds_read_b128 v[142:145], v131
	ds_read_b128 v[150:153], v229 offset:20480
	s_waitcnt lgkmcnt(1)
	v_mfma_f32_32x32x16_bf16 v[48:63], v[142:145], v[146:149], v[48:63]
	s_waitcnt lgkmcnt(0)
	v_mfma_f32_32x32x16_bf16 v[32:47], v[142:145], v[150:153], v[32:47]
	ds_read_b128 v[142:145], v131 offset:4096
	s_waitcnt lgkmcnt(0)
	v_mfma_f32_32x32x16_bf16 v[16:31], v[142:145], v[146:149], v[16:31]
	v_mfma_f32_32x32x16_bf16 v[0:15], v[142:145], v[150:153], v[0:15]
	s_waitcnt vmcnt(24)
	ds_write_b128 v134, v[196:199] offset:32768
	ds_write_b128 v134, v[212:215] offset:49152
	ds_write_b128 v134, v[200:203] offset:36864
	ds_write_b128 v134, v[216:219] offset:53248
	ds_write_b128 v134, v[204:207] offset:40960
	ds_write_b128 v134, v[220:223] offset:57344
	ds_write_b128 v134, v[208:211] offset:45056
	ds_write_b128 v134, v[224:227] offset:61440
	s_waitcnt lgkmcnt(0)
	s_barrier
	global_load_dwordx4 v[196:199], v230, s[14:15] offset:896
	global_load_dwordx4 v[200:203], v230, s[16:17] offset:896
	global_load_dwordx4 v[204:207], v230, s[18:19] offset:896
	global_load_dwordx4 v[208:211], v230, s[20:21] offset:896
	global_load_dwordx4 v[212:215], v231, s[22:23] offset:896
	global_load_dwordx4 v[216:219], v231, s[54:55] offset:896
	global_load_dwordx4 v[220:223], v231, s[72:73] offset:896
	global_load_dwordx4 v[224:227], v231, s[74:75] offset:896
	ds_read_b128 v[142:145], v128 offset:32768
	ds_read_b128 v[146:149], v132 offset:49152
	ds_read_b128 v[150:153], v132 offset:53248
	s_waitcnt lgkmcnt(1)
	v_mfma_f32_32x32x16_bf16 v[48:63], v[142:145], v[146:149], v[48:63]
	s_waitcnt lgkmcnt(0)
	v_mfma_f32_32x32x16_bf16 v[32:47], v[142:145], v[150:153], v[32:47]
	ds_read_b128 v[142:145], v128 offset:36864
	s_waitcnt lgkmcnt(0)
	v_mfma_f32_32x32x16_bf16 v[16:31], v[142:145], v[146:149], v[16:31]
	ds_read_b128 v[146:149], v133 offset:49152
	v_mfma_f32_32x32x16_bf16 v[0:15], v[142:145], v[150:153], v[0:15]
	ds_read_b128 v[142:145], v129 offset:32768
	ds_read_b128 v[150:153], v133 offset:53248
	s_waitcnt lgkmcnt(1)
	v_mfma_f32_32x32x16_bf16 v[48:63], v[142:145], v[146:149], v[48:63]
	s_waitcnt lgkmcnt(0)
	v_mfma_f32_32x32x16_bf16 v[32:47], v[142:145], v[150:153], v[32:47]
	ds_read_b128 v[142:145], v129 offset:36864
	s_waitcnt lgkmcnt(0)
	v_mfma_f32_32x32x16_bf16 v[16:31], v[142:145], v[146:149], v[16:31]
	ds_read_b128 v[146:149], v228 offset:49152
	v_mfma_f32_32x32x16_bf16 v[0:15], v[142:145], v[150:153], v[0:15]
	ds_read_b128 v[142:145], v130 offset:32768
	ds_read_b128 v[150:153], v228 offset:53248
	s_waitcnt lgkmcnt(1)
	v_mfma_f32_32x32x16_bf16 v[48:63], v[142:145], v[146:149], v[48:63]
	s_waitcnt lgkmcnt(0)
	v_mfma_f32_32x32x16_bf16 v[32:47], v[142:145], v[150:153], v[32:47]
	ds_read_b128 v[142:145], v130 offset:36864
	s_waitcnt lgkmcnt(0)
	v_mfma_f32_32x32x16_bf16 v[16:31], v[142:145], v[146:149], v[16:31]
	ds_read_b128 v[146:149], v229 offset:49152
	v_mfma_f32_32x32x16_bf16 v[0:15], v[142:145], v[150:153], v[0:15]
	ds_read_b128 v[142:145], v131 offset:32768
	ds_read_b128 v[150:153], v229 offset:53248
	s_waitcnt lgkmcnt(1)
	v_mfma_f32_32x32x16_bf16 v[48:63], v[142:145], v[146:149], v[48:63]
	s_waitcnt lgkmcnt(0)
	v_mfma_f32_32x32x16_bf16 v[32:47], v[142:145], v[150:153], v[32:47]
	ds_read_b128 v[142:145], v131 offset:36864
	s_waitcnt lgkmcnt(0)
	v_mfma_f32_32x32x16_bf16 v[16:31], v[142:145], v[146:149], v[16:31]
	v_mfma_f32_32x32x16_bf16 v[0:15], v[142:145], v[150:153], v[0:15]
	s_waitcnt vmcnt(24)
	ds_write_b128 v134, v[64:67]
	ds_write_b128 v134, v[80:83] offset:16384
	ds_write_b128 v134, v[68:71] offset:4096
	ds_write_b128 v134, v[84:87] offset:20480
	ds_write_b128 v134, v[72:75] offset:8192
	ds_write_b128 v134, v[88:91] offset:24576
	ds_write_b128 v134, v[76:79] offset:12288
	ds_write_b128 v134, v[92:95] offset:28672
	s_waitcnt lgkmcnt(0)
	s_barrier
	global_load_dwordx4 v[64:67], v232, s[80:81]
	global_load_dwordx4 v[68:71], v232, s[86:87]
	global_load_dwordx4 v[72:75], v232, s[40:41]
	global_load_dwordx4 v[76:79], v232, s[44:45]
	global_load_dwordx4 v[80:83], v231, s[22:23] offset:1024
	global_load_dwordx4 v[84:87], v231, s[54:55] offset:1024
	global_load_dwordx4 v[88:91], v231, s[72:73] offset:1024
	global_load_dwordx4 v[92:95], v231, s[74:75] offset:1024
	ds_read_b128 v[142:145], v128
	ds_read_b128 v[146:149], v132 offset:16384
	ds_read_b128 v[150:153], v132 offset:20480
	s_waitcnt lgkmcnt(1)
	v_mfma_f32_32x32x16_bf16 v[48:63], v[142:145], v[146:149], v[48:63]
	s_waitcnt lgkmcnt(0)
	v_mfma_f32_32x32x16_bf16 v[32:47], v[142:145], v[150:153], v[32:47]
	ds_read_b128 v[142:145], v128 offset:4096
	s_waitcnt lgkmcnt(0)
	v_mfma_f32_32x32x16_bf16 v[16:31], v[142:145], v[146:149], v[16:31]
	ds_read_b128 v[146:149], v133 offset:16384
	v_mfma_f32_32x32x16_bf16 v[0:15], v[142:145], v[150:153], v[0:15]
	ds_read_b128 v[142:145], v129
	ds_read_b128 v[150:153], v133 offset:20480
	s_waitcnt lgkmcnt(1)
	v_mfma_f32_32x32x16_bf16 v[48:63], v[142:145], v[146:149], v[48:63]
	s_waitcnt lgkmcnt(0)
	v_mfma_f32_32x32x16_bf16 v[32:47], v[142:145], v[150:153], v[32:47]
	ds_read_b128 v[142:145], v129 offset:4096
	s_waitcnt lgkmcnt(0)
	v_mfma_f32_32x32x16_bf16 v[16:31], v[142:145], v[146:149], v[16:31]
	ds_read_b128 v[146:149], v228 offset:16384
	v_mfma_f32_32x32x16_bf16 v[0:15], v[142:145], v[150:153], v[0:15]
	ds_read_b128 v[142:145], v130
	ds_read_b128 v[150:153], v228 offset:20480
	s_waitcnt lgkmcnt(1)
	v_mfma_f32_32x32x16_bf16 v[48:63], v[142:145], v[146:149], v[48:63]
	s_waitcnt lgkmcnt(0)
	v_mfma_f32_32x32x16_bf16 v[32:47], v[142:145], v[150:153], v[32:47]
	ds_read_b128 v[142:145], v130 offset:4096
	s_waitcnt lgkmcnt(0)
	v_mfma_f32_32x32x16_bf16 v[16:31], v[142:145], v[146:149], v[16:31]
	ds_read_b128 v[146:149], v229 offset:16384
	v_mfma_f32_32x32x16_bf16 v[0:15], v[142:145], v[150:153], v[0:15]
	ds_read_b128 v[142:145], v131
	ds_read_b128 v[150:153], v229 offset:20480
	s_waitcnt lgkmcnt(1)
	v_mfma_f32_32x32x16_bf16 v[48:63], v[142:145], v[146:149], v[48:63]
	s_waitcnt lgkmcnt(0)
	v_mfma_f32_32x32x16_bf16 v[32:47], v[142:145], v[150:153], v[32:47]
	ds_read_b128 v[142:145], v131 offset:4096
	s_waitcnt lgkmcnt(0)
	v_mfma_f32_32x32x16_bf16 v[16:31], v[142:145], v[146:149], v[16:31]
	v_mfma_f32_32x32x16_bf16 v[0:15], v[142:145], v[150:153], v[0:15]
	s_waitcnt vmcnt(24)
	ds_write_b128 v134, v[96:99] offset:32768
	ds_write_b128 v134, v[112:115] offset:49152
	ds_write_b128 v134, v[100:103] offset:36864
	ds_write_b128 v134, v[116:119] offset:53248
	ds_write_b128 v134, v[104:107] offset:40960
	ds_write_b128 v134, v[120:123] offset:57344
	ds_write_b128 v134, v[108:111] offset:45056
	ds_write_b128 v134, v[124:127] offset:61440
	s_waitcnt lgkmcnt(0)
	s_barrier
	global_load_dwordx4 v[96:99], v232, s[80:81] offset:128
	global_load_dwordx4 v[100:103], v232, s[86:87] offset:128
	global_load_dwordx4 v[104:107], v232, s[40:41] offset:128
	global_load_dwordx4 v[108:111], v232, s[44:45] offset:128
	global_load_dwordx4 v[112:115], v231, s[22:23] offset:1152
	global_load_dwordx4 v[116:119], v231, s[54:55] offset:1152
	global_load_dwordx4 v[120:123], v231, s[72:73] offset:1152
	global_load_dwordx4 v[124:127], v231, s[74:75] offset:1152
	ds_read_b128 v[142:145], v128 offset:32768
	ds_read_b128 v[146:149], v132 offset:49152
	ds_read_b128 v[150:153], v132 offset:53248
	s_waitcnt lgkmcnt(1)
	v_mfma_f32_32x32x16_bf16 v[48:63], v[142:145], v[146:149], v[48:63]
	s_waitcnt lgkmcnt(0)
	v_mfma_f32_32x32x16_bf16 v[32:47], v[142:145], v[150:153], v[32:47]
	ds_read_b128 v[142:145], v128 offset:36864
	s_waitcnt lgkmcnt(0)
	v_mfma_f32_32x32x16_bf16 v[16:31], v[142:145], v[146:149], v[16:31]
	ds_read_b128 v[146:149], v133 offset:49152
	v_mfma_f32_32x32x16_bf16 v[0:15], v[142:145], v[150:153], v[0:15]
	ds_read_b128 v[142:145], v129 offset:32768
	ds_read_b128 v[150:153], v133 offset:53248
	s_waitcnt lgkmcnt(1)
	v_mfma_f32_32x32x16_bf16 v[48:63], v[142:145], v[146:149], v[48:63]
	s_waitcnt lgkmcnt(0)
	v_mfma_f32_32x32x16_bf16 v[32:47], v[142:145], v[150:153], v[32:47]
	ds_read_b128 v[142:145], v129 offset:36864
	s_waitcnt lgkmcnt(0)
	v_mfma_f32_32x32x16_bf16 v[16:31], v[142:145], v[146:149], v[16:31]
	ds_read_b128 v[146:149], v228 offset:49152
	v_mfma_f32_32x32x16_bf16 v[0:15], v[142:145], v[150:153], v[0:15]
	ds_read_b128 v[142:145], v130 offset:32768
	ds_read_b128 v[150:153], v228 offset:53248
	s_waitcnt lgkmcnt(1)
	v_mfma_f32_32x32x16_bf16 v[48:63], v[142:145], v[146:149], v[48:63]
	s_waitcnt lgkmcnt(0)
	v_mfma_f32_32x32x16_bf16 v[32:47], v[142:145], v[150:153], v[32:47]
	ds_read_b128 v[142:145], v130 offset:36864
	s_waitcnt lgkmcnt(0)
	v_mfma_f32_32x32x16_bf16 v[16:31], v[142:145], v[146:149], v[16:31]
	ds_read_b128 v[146:149], v229 offset:49152
	v_mfma_f32_32x32x16_bf16 v[0:15], v[142:145], v[150:153], v[0:15]
	ds_read_b128 v[142:145], v131 offset:32768
	ds_read_b128 v[150:153], v229 offset:53248
	s_waitcnt lgkmcnt(1)
	v_mfma_f32_32x32x16_bf16 v[48:63], v[142:145], v[146:149], v[48:63]
	s_waitcnt lgkmcnt(0)
	v_mfma_f32_32x32x16_bf16 v[32:47], v[142:145], v[150:153], v[32:47]
	ds_read_b128 v[142:145], v131 offset:36864
	s_waitcnt lgkmcnt(0)
	v_mfma_f32_32x32x16_bf16 v[16:31], v[142:145], v[146:149], v[16:31]
	v_mfma_f32_32x32x16_bf16 v[0:15], v[142:145], v[150:153], v[0:15]
	s_waitcnt vmcnt(24)
	ds_write_b128 v134, v[160:163]
	ds_write_b128 v134, v[176:179] offset:16384
	ds_write_b128 v134, v[164:167] offset:4096
	ds_write_b128 v134, v[180:183] offset:20480
	ds_write_b128 v134, v[168:171] offset:8192
	ds_write_b128 v134, v[184:187] offset:24576
	ds_write_b128 v134, v[172:175] offset:12288
	ds_write_b128 v134, v[188:191] offset:28672
	s_waitcnt lgkmcnt(0)
	s_barrier
	global_load_dwordx4 v[160:163], v232, s[80:81] offset:256
	global_load_dwordx4 v[164:167], v232, s[86:87] offset:256
	global_load_dwordx4 v[168:171], v232, s[40:41] offset:256
	global_load_dwordx4 v[172:175], v232, s[44:45] offset:256
	global_load_dwordx4 v[176:179], v231, s[22:23] offset:1280
	global_load_dwordx4 v[180:183], v231, s[54:55] offset:1280
	global_load_dwordx4 v[184:187], v231, s[72:73] offset:1280
	global_load_dwordx4 v[188:191], v231, s[74:75] offset:1280
	ds_read_b128 v[142:145], v128
	ds_read_b128 v[146:149], v132 offset:16384
	ds_read_b128 v[150:153], v132 offset:20480
	s_waitcnt lgkmcnt(1)
	v_mfma_f32_32x32x16_bf16 v[48:63], v[142:145], v[146:149], v[48:63]
	s_waitcnt lgkmcnt(0)
	v_mfma_f32_32x32x16_bf16 v[32:47], v[142:145], v[150:153], v[32:47]
	ds_read_b128 v[142:145], v128 offset:4096
	s_waitcnt lgkmcnt(0)
	v_mfma_f32_32x32x16_bf16 v[16:31], v[142:145], v[146:149], v[16:31]
	ds_read_b128 v[146:149], v133 offset:16384
	v_mfma_f32_32x32x16_bf16 v[0:15], v[142:145], v[150:153], v[0:15]
	ds_read_b128 v[142:145], v129
	ds_read_b128 v[150:153], v133 offset:20480
	s_waitcnt lgkmcnt(1)
	v_mfma_f32_32x32x16_bf16 v[48:63], v[142:145], v[146:149], v[48:63]
	s_waitcnt lgkmcnt(0)
	v_mfma_f32_32x32x16_bf16 v[32:47], v[142:145], v[150:153], v[32:47]
	ds_read_b128 v[142:145], v129 offset:4096
	s_waitcnt lgkmcnt(0)
	v_mfma_f32_32x32x16_bf16 v[16:31], v[142:145], v[146:149], v[16:31]
	ds_read_b128 v[146:149], v228 offset:16384
	v_mfma_f32_32x32x16_bf16 v[0:15], v[142:145], v[150:153], v[0:15]
	ds_read_b128 v[142:145], v130
	ds_read_b128 v[150:153], v228 offset:20480
	s_waitcnt lgkmcnt(1)
	v_mfma_f32_32x32x16_bf16 v[48:63], v[142:145], v[146:149], v[48:63]
	s_waitcnt lgkmcnt(0)
	v_mfma_f32_32x32x16_bf16 v[32:47], v[142:145], v[150:153], v[32:47]
	ds_read_b128 v[142:145], v130 offset:4096
	s_waitcnt lgkmcnt(0)
	v_mfma_f32_32x32x16_bf16 v[16:31], v[142:145], v[146:149], v[16:31]
	ds_read_b128 v[146:149], v229 offset:16384
	v_mfma_f32_32x32x16_bf16 v[0:15], v[142:145], v[150:153], v[0:15]
	ds_read_b128 v[142:145], v131
	ds_read_b128 v[150:153], v229 offset:20480
	s_waitcnt lgkmcnt(1)
	v_mfma_f32_32x32x16_bf16 v[48:63], v[142:145], v[146:149], v[48:63]
	s_waitcnt lgkmcnt(0)
	v_mfma_f32_32x32x16_bf16 v[32:47], v[142:145], v[150:153], v[32:47]
	ds_read_b128 v[142:145], v131 offset:4096
	s_waitcnt lgkmcnt(0)
	v_mfma_f32_32x32x16_bf16 v[16:31], v[142:145], v[146:149], v[16:31]
	v_mfma_f32_32x32x16_bf16 v[0:15], v[142:145], v[150:153], v[0:15]
	s_waitcnt vmcnt(24)
	ds_write_b128 v134, v[196:199] offset:32768
	ds_write_b128 v134, v[212:215] offset:49152
	ds_write_b128 v134, v[200:203] offset:36864
	ds_write_b128 v134, v[216:219] offset:53248
	ds_write_b128 v134, v[204:207] offset:40960
	ds_write_b128 v134, v[220:223] offset:57344
	ds_write_b128 v134, v[208:211] offset:45056
	ds_write_b128 v134, v[224:227] offset:61440
	s_waitcnt lgkmcnt(0)
	s_barrier
	global_load_dwordx4 v[196:199], v232, s[80:81] offset:384
	global_load_dwordx4 v[200:203], v232, s[86:87] offset:384
	global_load_dwordx4 v[204:207], v232, s[40:41] offset:384
	global_load_dwordx4 v[208:211], v232, s[44:45] offset:384
	global_load_dwordx4 v[212:215], v231, s[22:23] offset:1408
	global_load_dwordx4 v[216:219], v231, s[54:55] offset:1408
	global_load_dwordx4 v[220:223], v231, s[72:73] offset:1408
	global_load_dwordx4 v[224:227], v231, s[74:75] offset:1408
	ds_read_b128 v[142:145], v128 offset:32768
	ds_read_b128 v[146:149], v132 offset:49152
	ds_read_b128 v[150:153], v132 offset:53248
	s_waitcnt lgkmcnt(1)
	v_mfma_f32_32x32x16_bf16 v[48:63], v[142:145], v[146:149], v[48:63]
	s_waitcnt lgkmcnt(0)
	v_mfma_f32_32x32x16_bf16 v[32:47], v[142:145], v[150:153], v[32:47]
	ds_read_b128 v[142:145], v128 offset:36864
	s_waitcnt lgkmcnt(0)
	v_mfma_f32_32x32x16_bf16 v[16:31], v[142:145], v[146:149], v[16:31]
	ds_read_b128 v[146:149], v133 offset:49152
	v_mfma_f32_32x32x16_bf16 v[0:15], v[142:145], v[150:153], v[0:15]
	ds_read_b128 v[142:145], v129 offset:32768
	ds_read_b128 v[150:153], v133 offset:53248
	s_waitcnt lgkmcnt(1)
	v_mfma_f32_32x32x16_bf16 v[48:63], v[142:145], v[146:149], v[48:63]
	s_waitcnt lgkmcnt(0)
	v_mfma_f32_32x32x16_bf16 v[32:47], v[142:145], v[150:153], v[32:47]
	ds_read_b128 v[142:145], v129 offset:36864
	s_waitcnt lgkmcnt(0)
	v_mfma_f32_32x32x16_bf16 v[16:31], v[142:145], v[146:149], v[16:31]
	ds_read_b128 v[146:149], v228 offset:49152
	v_mfma_f32_32x32x16_bf16 v[0:15], v[142:145], v[150:153], v[0:15]
	ds_read_b128 v[142:145], v130 offset:32768
	ds_read_b128 v[150:153], v228 offset:53248
	s_waitcnt lgkmcnt(1)
	v_mfma_f32_32x32x16_bf16 v[48:63], v[142:145], v[146:149], v[48:63]
	s_waitcnt lgkmcnt(0)
	v_mfma_f32_32x32x16_bf16 v[32:47], v[142:145], v[150:153], v[32:47]
	ds_read_b128 v[142:145], v130 offset:36864
	s_waitcnt lgkmcnt(0)
	v_mfma_f32_32x32x16_bf16 v[16:31], v[142:145], v[146:149], v[16:31]
	ds_read_b128 v[146:149], v229 offset:49152
	v_mfma_f32_32x32x16_bf16 v[0:15], v[142:145], v[150:153], v[0:15]
	ds_read_b128 v[142:145], v131 offset:32768
	ds_read_b128 v[150:153], v229 offset:53248
	s_waitcnt lgkmcnt(1)
	v_mfma_f32_32x32x16_bf16 v[48:63], v[142:145], v[146:149], v[48:63]
	s_waitcnt lgkmcnt(0)
	v_mfma_f32_32x32x16_bf16 v[32:47], v[142:145], v[150:153], v[32:47]
	ds_read_b128 v[142:145], v131 offset:36864
	s_waitcnt lgkmcnt(0)
	v_mfma_f32_32x32x16_bf16 v[16:31], v[142:145], v[146:149], v[16:31]
	v_mfma_f32_32x32x16_bf16 v[0:15], v[142:145], v[150:153], v[0:15]
	s_waitcnt vmcnt(24)
	ds_write_b128 v134, v[64:67]
	ds_write_b128 v134, v[80:83] offset:16384
	ds_write_b128 v134, v[68:71] offset:4096
	ds_write_b128 v134, v[84:87] offset:20480
	ds_write_b128 v134, v[72:75] offset:8192
	ds_write_b128 v134, v[88:91] offset:24576
	ds_write_b128 v134, v[76:79] offset:12288
	ds_write_b128 v134, v[92:95] offset:28672
	s_waitcnt lgkmcnt(0)
	s_barrier
	ds_read_b128 v[142:145], v128
	ds_read_b128 v[146:149], v132 offset:16384
	ds_read_b128 v[150:153], v132 offset:20480
	s_waitcnt lgkmcnt(1)
	v_mfma_f32_32x32x16_bf16 v[48:63], v[142:145], v[146:149], v[48:63]
	s_waitcnt lgkmcnt(0)
	v_mfma_f32_32x32x16_bf16 v[32:47], v[142:145], v[150:153], v[32:47]
	ds_read_b128 v[142:145], v128 offset:4096
	s_waitcnt lgkmcnt(0)
	v_mfma_f32_32x32x16_bf16 v[16:31], v[142:145], v[146:149], v[16:31]
	ds_read_b128 v[146:149], v133 offset:16384
	v_mfma_f32_32x32x16_bf16 v[0:15], v[142:145], v[150:153], v[0:15]
	ds_read_b128 v[142:145], v129
	ds_read_b128 v[150:153], v133 offset:20480
	s_waitcnt lgkmcnt(1)
	v_mfma_f32_32x32x16_bf16 v[48:63], v[142:145], v[146:149], v[48:63]
	s_waitcnt lgkmcnt(0)
	v_mfma_f32_32x32x16_bf16 v[32:47], v[142:145], v[150:153], v[32:47]
	ds_read_b128 v[142:145], v129 offset:4096
	s_waitcnt lgkmcnt(0)
	v_mfma_f32_32x32x16_bf16 v[16:31], v[142:145], v[146:149], v[16:31]
	ds_read_b128 v[146:149], v228 offset:16384
	v_mfma_f32_32x32x16_bf16 v[0:15], v[142:145], v[150:153], v[0:15]
	ds_read_b128 v[142:145], v130
	ds_read_b128 v[150:153], v228 offset:20480
	s_waitcnt lgkmcnt(1)
	v_mfma_f32_32x32x16_bf16 v[48:63], v[142:145], v[146:149], v[48:63]
	s_waitcnt lgkmcnt(0)
	v_mfma_f32_32x32x16_bf16 v[32:47], v[142:145], v[150:153], v[32:47]
	ds_read_b128 v[142:145], v130 offset:4096
	s_waitcnt lgkmcnt(0)
	v_mfma_f32_32x32x16_bf16 v[16:31], v[142:145], v[146:149], v[16:31]
	ds_read_b128 v[146:149], v229 offset:16384
	v_mfma_f32_32x32x16_bf16 v[0:15], v[142:145], v[150:153], v[0:15]
	ds_read_b128 v[142:145], v131
	ds_read_b128 v[150:153], v229 offset:20480
	s_waitcnt lgkmcnt(1)
	v_mfma_f32_32x32x16_bf16 v[48:63], v[142:145], v[146:149], v[48:63]
	s_waitcnt lgkmcnt(0)
	v_mfma_f32_32x32x16_bf16 v[32:47], v[142:145], v[150:153], v[32:47]
	ds_read_b128 v[142:145], v131 offset:4096
	s_waitcnt lgkmcnt(0)
	v_mfma_f32_32x32x16_bf16 v[16:31], v[142:145], v[146:149], v[16:31]
	v_mfma_f32_32x32x16_bf16 v[0:15], v[142:145], v[150:153], v[0:15]
	s_waitcnt vmcnt(16)
	ds_write_b128 v134, v[96:99] offset:32768
	ds_write_b128 v134, v[112:115] offset:49152
	ds_write_b128 v134, v[100:103] offset:36864
	ds_write_b128 v134, v[116:119] offset:53248
	ds_write_b128 v134, v[104:107] offset:40960
	ds_write_b128 v134, v[120:123] offset:57344
	ds_write_b128 v134, v[108:111] offset:45056
	ds_write_b128 v134, v[124:127] offset:61440
	s_waitcnt lgkmcnt(0)
	s_barrier
	ds_read_b128 v[142:145], v128 offset:32768
	ds_read_b128 v[146:149], v132 offset:49152
	ds_read_b128 v[150:153], v132 offset:53248
	s_waitcnt lgkmcnt(1)
	v_mfma_f32_32x32x16_bf16 v[48:63], v[142:145], v[146:149], v[48:63]
	s_waitcnt lgkmcnt(0)
	v_mfma_f32_32x32x16_bf16 v[32:47], v[142:145], v[150:153], v[32:47]
	ds_read_b128 v[142:145], v128 offset:36864
	s_waitcnt lgkmcnt(0)
	v_mfma_f32_32x32x16_bf16 v[16:31], v[142:145], v[146:149], v[16:31]
	ds_read_b128 v[146:149], v133 offset:49152
	v_mfma_f32_32x32x16_bf16 v[0:15], v[142:145], v[150:153], v[0:15]
	ds_read_b128 v[142:145], v129 offset:32768
	ds_read_b128 v[150:153], v133 offset:53248
	s_waitcnt lgkmcnt(1)
	v_mfma_f32_32x32x16_bf16 v[48:63], v[142:145], v[146:149], v[48:63]
	s_waitcnt lgkmcnt(0)
	v_mfma_f32_32x32x16_bf16 v[32:47], v[142:145], v[150:153], v[32:47]
	ds_read_b128 v[142:145], v129 offset:36864
	s_waitcnt lgkmcnt(0)
	v_mfma_f32_32x32x16_bf16 v[16:31], v[142:145], v[146:149], v[16:31]
	ds_read_b128 v[146:149], v228 offset:49152
	v_mfma_f32_32x32x16_bf16 v[0:15], v[142:145], v[150:153], v[0:15]
	ds_read_b128 v[142:145], v130 offset:32768
	ds_read_b128 v[150:153], v228 offset:53248
	s_waitcnt lgkmcnt(1)
	v_mfma_f32_32x32x16_bf16 v[48:63], v[142:145], v[146:149], v[48:63]
	s_waitcnt lgkmcnt(0)
	v_mfma_f32_32x32x16_bf16 v[32:47], v[142:145], v[150:153], v[32:47]
	ds_read_b128 v[142:145], v130 offset:36864
	s_waitcnt lgkmcnt(0)
	v_mfma_f32_32x32x16_bf16 v[16:31], v[142:145], v[146:149], v[16:31]
	ds_read_b128 v[146:149], v229 offset:49152
	v_mfma_f32_32x32x16_bf16 v[0:15], v[142:145], v[150:153], v[0:15]
	ds_read_b128 v[142:145], v131 offset:32768
	ds_read_b128 v[150:153], v229 offset:53248
	s_waitcnt lgkmcnt(1)
	v_mfma_f32_32x32x16_bf16 v[48:63], v[142:145], v[146:149], v[48:63]
	s_waitcnt lgkmcnt(0)
	v_mfma_f32_32x32x16_bf16 v[32:47], v[142:145], v[150:153], v[32:47]
	ds_read_b128 v[142:145], v131 offset:36864
	s_waitcnt lgkmcnt(0)
	v_mfma_f32_32x32x16_bf16 v[16:31], v[142:145], v[146:149], v[16:31]
	v_mfma_f32_32x32x16_bf16 v[0:15], v[142:145], v[150:153], v[0:15]
	s_waitcnt vmcnt(8)
	ds_write_b128 v134, v[160:163]
	ds_write_b128 v134, v[176:179] offset:16384
	ds_write_b128 v134, v[164:167] offset:4096
	ds_write_b128 v134, v[180:183] offset:20480
	ds_write_b128 v134, v[168:171] offset:8192
	ds_write_b128 v134, v[184:187] offset:24576
	ds_write_b128 v134, v[172:175] offset:12288
	ds_write_b128 v134, v[188:191] offset:28672
	s_waitcnt lgkmcnt(0)
	s_barrier
	ds_read_b128 v[142:145], v128
	ds_read_b128 v[146:149], v132 offset:16384
	ds_read_b128 v[150:153], v132 offset:20480
	s_waitcnt lgkmcnt(1)
	v_mfma_f32_32x32x16_bf16 v[48:63], v[142:145], v[146:149], v[48:63]
	s_waitcnt lgkmcnt(0)
	v_mfma_f32_32x32x16_bf16 v[32:47], v[142:145], v[150:153], v[32:47]
	ds_read_b128 v[142:145], v128 offset:4096
	s_waitcnt lgkmcnt(0)
	v_mfma_f32_32x32x16_bf16 v[16:31], v[142:145], v[146:149], v[16:31]
	ds_read_b128 v[146:149], v133 offset:16384
	v_mfma_f32_32x32x16_bf16 v[0:15], v[142:145], v[150:153], v[0:15]
	ds_read_b128 v[142:145], v129
	ds_read_b128 v[150:153], v133 offset:20480
	s_waitcnt lgkmcnt(1)
	v_mfma_f32_32x32x16_bf16 v[48:63], v[142:145], v[146:149], v[48:63]
	s_waitcnt lgkmcnt(0)
	v_mfma_f32_32x32x16_bf16 v[32:47], v[142:145], v[150:153], v[32:47]
	ds_read_b128 v[142:145], v129 offset:4096
	s_waitcnt lgkmcnt(0)
	v_mfma_f32_32x32x16_bf16 v[16:31], v[142:145], v[146:149], v[16:31]
	ds_read_b128 v[146:149], v228 offset:16384
	v_mfma_f32_32x32x16_bf16 v[0:15], v[142:145], v[150:153], v[0:15]
	ds_read_b128 v[142:145], v130
	ds_read_b128 v[150:153], v228 offset:20480
	s_waitcnt lgkmcnt(1)
	v_mfma_f32_32x32x16_bf16 v[48:63], v[142:145], v[146:149], v[48:63]
	s_waitcnt lgkmcnt(0)
	v_mfma_f32_32x32x16_bf16 v[32:47], v[142:145], v[150:153], v[32:47]
	ds_read_b128 v[142:145], v130 offset:4096
	s_waitcnt lgkmcnt(0)
	v_mfma_f32_32x32x16_bf16 v[16:31], v[142:145], v[146:149], v[16:31]
	ds_read_b128 v[146:149], v229 offset:16384
	v_mfma_f32_32x32x16_bf16 v[0:15], v[142:145], v[150:153], v[0:15]
	ds_read_b128 v[142:145], v131
	ds_read_b128 v[150:153], v229 offset:20480
	s_waitcnt lgkmcnt(1)
	v_mfma_f32_32x32x16_bf16 v[48:63], v[142:145], v[146:149], v[48:63]
	s_waitcnt lgkmcnt(0)
	v_mfma_f32_32x32x16_bf16 v[32:47], v[142:145], v[150:153], v[32:47]
	ds_read_b128 v[142:145], v131 offset:4096
	s_waitcnt lgkmcnt(0)
	v_mfma_f32_32x32x16_bf16 v[16:31], v[142:145], v[146:149], v[16:31]
	v_mfma_f32_32x32x16_bf16 v[0:15], v[142:145], v[150:153], v[0:15]
	s_waitcnt vmcnt(0)
	ds_write_b128 v134, v[196:199] offset:32768
	ds_write_b128 v134, v[212:215] offset:49152
	ds_write_b128 v134, v[200:203] offset:36864
	ds_write_b128 v134, v[216:219] offset:53248
	ds_write_b128 v134, v[204:207] offset:40960
	ds_write_b128 v134, v[220:223] offset:57344
	ds_write_b128 v134, v[208:211] offset:45056
	ds_write_b128 v134, v[224:227] offset:61440
	s_waitcnt lgkmcnt(0)
	s_barrier
	ds_read_b128 v[142:145], v128 offset:32768
	ds_read_b128 v[146:149], v132 offset:49152
	ds_read_b128 v[150:153], v132 offset:53248
	s_waitcnt lgkmcnt(1)
	v_mfma_f32_32x32x16_bf16 v[48:63], v[142:145], v[146:149], v[48:63]
	s_waitcnt lgkmcnt(0)
	v_mfma_f32_32x32x16_bf16 v[32:47], v[142:145], v[150:153], v[32:47]
	ds_read_b128 v[142:145], v128 offset:36864
	s_waitcnt lgkmcnt(0)
	v_mfma_f32_32x32x16_bf16 v[16:31], v[142:145], v[146:149], v[16:31]
	ds_read_b128 v[146:149], v133 offset:49152
	v_mfma_f32_32x32x16_bf16 v[0:15], v[142:145], v[150:153], v[0:15]
	ds_read_b128 v[142:145], v129 offset:32768
	ds_read_b128 v[150:153], v133 offset:53248
	s_waitcnt lgkmcnt(1)
	v_mfma_f32_32x32x16_bf16 v[48:63], v[142:145], v[146:149], v[48:63]
	s_waitcnt lgkmcnt(0)
	v_mfma_f32_32x32x16_bf16 v[32:47], v[142:145], v[150:153], v[32:47]
	ds_read_b128 v[142:145], v129 offset:36864
	s_waitcnt lgkmcnt(0)
	v_mfma_f32_32x32x16_bf16 v[16:31], v[142:145], v[146:149], v[16:31]
	ds_read_b128 v[146:149], v228 offset:49152
	v_mfma_f32_32x32x16_bf16 v[0:15], v[142:145], v[150:153], v[0:15]
	ds_read_b128 v[142:145], v130 offset:32768
	ds_read_b128 v[150:153], v228 offset:53248
	s_waitcnt lgkmcnt(1)
	v_mfma_f32_32x32x16_bf16 v[48:63], v[142:145], v[146:149], v[48:63]
	s_waitcnt lgkmcnt(0)
	v_mfma_f32_32x32x16_bf16 v[32:47], v[142:145], v[150:153], v[32:47]
	ds_read_b128 v[142:145], v130 offset:36864
	s_waitcnt lgkmcnt(0)
	v_mfma_f32_32x32x16_bf16 v[16:31], v[142:145], v[146:149], v[16:31]
	ds_read_b128 v[146:149], v229 offset:49152
	v_mfma_f32_32x32x16_bf16 v[0:15], v[142:145], v[150:153], v[0:15]
	ds_read_b128 v[142:145], v131 offset:32768
	ds_read_b128 v[150:153], v229 offset:53248
	s_waitcnt lgkmcnt(1)
	v_mfma_f32_32x32x16_bf16 v[48:63], v[142:145], v[146:149], v[48:63]
	s_waitcnt lgkmcnt(0)
	v_mfma_f32_32x32x16_bf16 v[32:47], v[142:145], v[150:153], v[32:47]
	ds_read_b128 v[142:145], v131 offset:36864
	s_waitcnt lgkmcnt(0)
	v_mfma_f32_32x32x16_bf16 v[16:31], v[142:145], v[146:149], v[16:31]
	v_mfma_f32_32x32x16_bf16 v[0:15], v[142:145], v[150:153], v[0:15]
	s_barrier
	s_waitcnt vmcnt(7)
	v_mov_b32_e32 v64, v235
	s_mov_b32 s0, 0x7fffc0
	v_lshrrev_b32_e32 v66, 3, v64
	v_lshrrev_b32_e32 v65, 1, v64
	v_and_b32_e32 v66, 4, v66
	v_and_or_b32 v65, v65, s0, v66
	v_and_b32_e32 v64, 0x5f, v64
	v_lshlrev_b32_e32 v65, 9, v65
	v_lshlrev_b32_e32 v64, 2, v64
	v_add3_u32 v64, s13, v65, v64
	ds_write2_b32 v64, v48, v32 offset1:32
	ds_write2_b32 v64, v49, v33 offset0:128 offset1:160
	v_add_u32_e32 v32, 0x400, v64
	ds_write2_b32 v32, v50, v34 offset1:32
	ds_write2_b32 v32, v51, v35 offset0:128 offset1:160
	v_add_u32_e32 v32, 0x1000, v64
	ds_write2_b32 v32, v52, v36 offset1:32
	ds_write2_b32 v32, v53, v37 offset0:128 offset1:160
	v_add_u32_e32 v32, 0x1400, v64
	ds_write2_b32 v32, v54, v38 offset1:32
	ds_write2_b32 v32, v55, v39 offset0:128 offset1:160
	v_add_u32_e32 v32, 0x2000, v64
	ds_write2_b32 v32, v56, v40 offset1:32
	ds_write2_b32 v32, v57, v41 offset0:128 offset1:160
	v_add_u32_e32 v32, 0x2400, v64
	ds_write2_b32 v32, v58, v42 offset1:32
	ds_write2_b32 v32, v59, v43 offset0:128 offset1:160
	v_add_u32_e32 v32, 0x3000, v64
	ds_write2_b32 v32, v60, v44 offset1:32
	ds_write2_b32 v32, v61, v45 offset0:128 offset1:160
	v_add_u32_e32 v32, 0x3400, v64
	ds_write2_b32 v32, v62, v46 offset1:32
	ds_write2_b32 v32, v63, v47 offset0:128 offset1:160
	v_add_u32_e32 v32, 0x4000, v64
	ds_write2_b32 v32, v16, v0 offset1:32
	ds_write2_b32 v32, v17, v1 offset0:128 offset1:160
	v_add_u32_e32 v0, 0x4400, v64
	ds_write2_b32 v0, v18, v2 offset1:32
	ds_write2_b32 v0, v19, v3 offset0:128 offset1:160
	v_add_u32_e32 v0, 0x5000, v64
	ds_write2_b32 v0, v20, v4 offset1:32
	ds_write2_b32 v0, v21, v5 offset0:128 offset1:160
	v_add_u32_e32 v0, 0x5400, v64
	s_lshl_b32 s0, s2, 5
	ds_write2_b32 v0, v22, v6 offset1:32
	ds_write2_b32 v0, v23, v7 offset0:128 offset1:160
	v_add_u32_e32 v0, 0x6000, v64
	s_add_u32 s0, s60, s0
	ds_write2_b32 v0, v24, v8 offset1:32
	ds_write2_b32 v0, v25, v9 offset0:128 offset1:160
	v_add_u32_e32 v0, 0x6400, v64
	s_mul_i32 s90, s2, 0x3000
	s_addc_u32 s1, s61, 0
	s_lshl_b32 s2, s2, 6
	ds_write2_b32 v0, v26, v10 offset1:32
	ds_write2_b32 v0, v27, v11 offset0:128 offset1:160
	v_add_u32_e32 v0, 0x7000, v64
	s_add_u32 s2, s36, s2
	ds_write2_b32 v0, v28, v12 offset1:32
	ds_write2_b32 v0, v29, v13 offset0:128 offset1:160
	v_add_u32_e32 v0, 0x7400, v64
	s_addc_u32 s3, s37, 0
	s_mov_b32 s40, 0
	ds_write2_b32 v0, v30, v14 offset1:32
	ds_write2_b32 v0, v31, v15 offset0:128 offset1:160
	v_lshlrev_b32_e32 v228, 3, v235
	v_and_b32_e32 v226, 0x78, v228
	v_or_b32_e32 v226, s38, v226
	v_lshrrev_b32_e32 v226, 4, v226
	v_ashrrev_i32_e32 v224, 4, v235
	v_add_u32_e32 v224, s39, v224
	v_lshl_or_b32 v224, v224, 5, v226
	v_ashrrev_i32_e32 v225, 31, v224
	v_lshl_add_u64 v[224:225], s[90:91], 0, v[224:225]
	v_lshlrev_b64 v[224:225], 5, v[224:225]
	v_lshl_add_u64 v[224:225], s[68:69], 0, v[224:225]
	v_and_b32_e32 v228, 8, v228
	v_lshlrev_b32_e32 v226, 1, v228
	v_mov_b32_e32 v227, 0
	v_lshl_add_u64 v[224:225], v[224:225], 0, v[226:227]
	v_lshlrev_b32_e32 v228, 2, v228
	global_load_dwordx4 v[216:219], v228, s[2:3] offset:16
	global_load_dwordx4 v[212:215], v228, s[2:3]
	global_load_dwordx4 v[220:223], v[224:225], off
	s_mov_b32 s14, 0x4000
	s_mov_b32 s15, 0
	s_waitcnt lgkmcnt(0)
	s_barrier
	s_waitcnt vmcnt(0)

.LBB0_763:
	v_readlane_b32 s1, v255, 17
	v_readfirstlane_b32 s0, v234
	s_mul_i32 s1, s39, s1
	v_readlane_b32 s8, v255, 19
	s_lshr_b32 s0, s0, 8
	s_add_i32 s10, s1, s8
	s_add_i32 s10, s10, s0
	s_cmp_gt_u32 s10, 47
	s_mov_b64 s[0:1], -1
	s_cbranch_scc1 .LBB0_762
	s_and_b32 s40, s10, 0xff
	s_mul_i32 s0, s40, 0xab
	s_lshr_b32 s41, s0, 11
	s_mul_i32 s0, s41, 12
	s_sub_i32 s0, s10, s0
	s_and_b32 s0, s0, 0xff
	v_readlane_b32 s1, v255, 36
	s_add_i32 s0, s1, s0
	v_mov_b32_e32 v48, v235
	s_lshl_b32 s0, s0, 17
	s_add_u32 s0, s60, s0
	v_ashrrev_i32_e32 v32, 3, v48
	v_ashrrev_i32_e32 v33, 31, v32
	s_addc_u32 s1, s61, 0
	s_mov_b64 s[24:25], s[0:1]
	s_lshl_b32 s10, s41, 17
	v_lshlrev_b64 v[34:35], 10, v[32:33]
	v_lshlrev_b32_e32 v33, 4, v48
	s_add_u32 s44, s37, s10
	v_lshl_add_u64 v[0:1], s[0:1], 0, v[34:35]
	v_and_b32_e32 v192, 0x70, v33
	v_lshlrev_b32_e32 v230, 10, v32
	v_or_b32_e32 v230, v230, v192
	s_addc_u32 s45, s38, 0
	s_mov_b64 s[72:73], s[44:45]
	v_lshl_add_u64 v[128:129], v[0:1], 0, v[192:193]
	v_lshl_add_u64 v[0:1], s[44:45], 0, v[34:35]
	v_add_co_u32_e32 v36, vcc, s88, v128
	v_lshl_add_u64 v[130:131], v[0:1], 0, v[192:193]
	s_nop 0
	v_addc_co_u32_e32 v37, vcc, 0, v129, vcc
	v_add_co_u32_e32 v38, vcc, s88, v130
	v_addc_co_u32_e32 v39, vcc, 0, v131, vcc
	v_add_co_u32_e32 v40, vcc, s97, v128
	s_nop 0
	v_addc_co_u32_e32 v41, vcc, 0, v129, vcc
	v_add_co_u32_e32 v42, vcc, s97, v130
	s_nop 0
	v_addc_co_u32_e32 v43, vcc, 0, v131, vcc
	v_add_co_u32_e32 v44, vcc, s76, v128
	s_nop 0
	v_addc_co_u32_e32 v45, vcc, 0, v129, vcc
	v_add_co_u32_e32 v46, vcc, s76, v130
	s_nop 0
	v_addc_co_u32_e32 v47, vcc, 0, v131, vcc
	v_and_b32_e32 v49, 31, v48
	v_lshrrev_b32_e32 v52, 1, v48
	s_mov_b32 s0, 0x1ffffc0
	v_lshrrev_b32_e32 v50, 5, v48
	v_bfe_u32 v51, v48, 5, 1
	v_bfe_u32 v53, v48, 1, 3
	v_lshlrev_b32_e32 v54, 7, v48
	v_lshlrev_b32_e32 v32, 7, v32
	v_xor_b32_e32 v33, v33, v48
	v_and_or_b32 v48, v52, s0, v49
	s_movk_i32 s0, 0x70
	v_and_b32_e32 v49, 0x2f80, v54
	v_and_or_b32 v54, v33, s0, v32
	v_add_u32_e32 v138, s36, v54
	v_bitop3_b32 v50, v50, v53, 1 bitop3:0x6c
	v_bitop3_b32 v52, v51, v53, 2 bitop3:0x36
	v_lshl_add_u64 v[32:33], s[60:61], 0, v[34:35]
	s_mov_b32 s43, 0
	v_lshl_add_u32 v134, v48, 7, s36
	v_add_u32_e32 v135, s36, v49
	v_lshlrev_b32_e32 v136, 4, v50
	v_lshlrev_b32_e32 v137, 4, v52
	v_lshl_add_u64 v[132:133], v[32:33], 0, v[192:193]
	v_bitop3_b32 v0, v51, v53, 4 bitop3:0x36
	v_lshlrev_b32_e32 v139, 4, v0
	v_bitop3_b32 v0, v51, v53, 6 bitop3:0x36
	v_lshlrev_b32_e32 v140, 4, v0
	s_add_u32 s30, s24, 0x8000
	s_addc_u32 s31, s25, 0
	s_add_u32 s50, s24, 0x10000
	s_addc_u32 s51, s25, 0
	s_add_u32 s54, s24, 0x18000
	s_addc_u32 s55, s25, 0
	s_add_u32 s74, s72, 0x8000
	s_addc_u32 s75, s73, 0
	s_add_u32 s80, s72, 0x10000
	s_addc_u32 s81, s73, 0
	s_add_u32 s86, s72, 0x18000
	s_addc_u32 s87, s73, 0
	global_load_dwordx4 v[64:67], v230, s[24:25]
	global_load_dwordx4 v[68:71], v230, s[30:31]
	global_load_dwordx4 v[72:75], v230, s[50:51]
	global_load_dwordx4 v[76:79], v230, s[54:55]
	global_load_dwordx4 v[80:83], v230, s[72:73]
	global_load_dwordx4 v[84:87], v230, s[74:75]
	global_load_dwordx4 v[88:91], v230, s[80:81]
	global_load_dwordx4 v[92:95], v230, s[86:87]
	global_load_dwordx4 v[96:99], v230, s[24:25] offset:128
	global_load_dwordx4 v[100:103], v230, s[30:31] offset:128
	global_load_dwordx4 v[104:107], v230, s[50:51] offset:128
	global_load_dwordx4 v[108:111], v230, s[54:55] offset:128
	global_load_dwordx4 v[112:115], v230, s[72:73] offset:128
	global_load_dwordx4 v[116:119], v230, s[74:75] offset:128
	global_load_dwordx4 v[120:123], v230, s[80:81] offset:128
	global_load_dwordx4 v[124:127], v230, s[86:87] offset:128
	global_load_dwordx4 v[160:163], v230, s[24:25] offset:256
	global_load_dwordx4 v[164:167], v230, s[30:31] offset:256
	global_load_dwordx4 v[168:171], v230, s[50:51] offset:256
	global_load_dwordx4 v[172:175], v230, s[54:55] offset:256
	global_load_dwordx4 v[176:179], v230, s[72:73] offset:256
	global_load_dwordx4 v[180:183], v230, s[74:75] offset:256
	global_load_dwordx4 v[184:187], v230, s[80:81] offset:256
	global_load_dwordx4 v[188:191], v230, s[86:87] offset:256
	global_load_dwordx4 v[196:199], v230, s[24:25] offset:384
	global_load_dwordx4 v[200:203], v230, s[30:31] offset:384
	global_load_dwordx4 v[204:207], v230, s[50:51] offset:384
	global_load_dwordx4 v[208:211], v230, s[54:55] offset:384
	global_load_dwordx4 v[212:215], v230, s[72:73] offset:384
	global_load_dwordx4 v[216:219], v230, s[74:75] offset:384
	global_load_dwordx4 v[220:223], v230, s[80:81] offset:384
	global_load_dwordx4 v[224:227], v230, s[86:87] offset:384
	v_add_u32_e32 v128, v134, v136
	v_add_u32_e32 v132, v135, v136
	v_add_u32_e32 v129, v134, v137
	v_add_u32_e32 v133, v135, v137
	v_add_u32_e32 v130, v134, v139
	v_add_u32_e32 v228, v135, v139
	v_add_u32_e32 v131, v134, v140
	v_add_u32_e32 v229, v135, v140
	v_mov_b32_e32 v0, 0
	v_mov_b32_e32 v1, v0
	v_mov_b32_e32 v2, v0
	v_mov_b32_e32 v3, v0
	v_mov_b32_e32 v4, v0
	v_mov_b32_e32 v5, v0
	v_mov_b32_e32 v6, v0
	v_mov_b32_e32 v7, v0
	v_mov_b32_e32 v8, v0
	v_mov_b32_e32 v9, v0
	v_mov_b32_e32 v10, v0
	v_mov_b32_e32 v11, v0
	v_mov_b32_e32 v12, v0
	v_mov_b32_e32 v13, v0
	v_mov_b32_e32 v14, v0
	v_mov_b32_e32 v15, v0
	v_mov_b32_e32 v16, v0
	v_mov_b32_e32 v17, v0
	v_mov_b32_e32 v18, v0
	v_mov_b32_e32 v19, v0
	v_mov_b32_e32 v20, v0
	v_mov_b32_e32 v21, v0
	v_mov_b32_e32 v22, v0
	v_mov_b32_e32 v23, v0
	v_mov_b32_e32 v24, v0
	v_mov_b32_e32 v25, v0
	v_mov_b32_e32 v26, v0
	v_mov_b32_e32 v27, v0
	v_mov_b32_e32 v28, v0
	v_mov_b32_e32 v29, v0
	v_mov_b32_e32 v30, v0
	v_mov_b32_e32 v31, v0
	v_mov_b32_e32 v32, v0
	v_mov_b32_e32 v33, v0
	v_mov_b32_e32 v34, v0
	v_mov_b32_e32 v35, v0
	v_mov_b32_e32 v36, v0
	v_mov_b32_e32 v37, v0
	v_mov_b32_e32 v38, v0
	v_mov_b32_e32 v39, v0
	v_mov_b32_e32 v40, v0
	v_mov_b32_e32 v41, v0
	v_mov_b32_e32 v42, v0
	v_mov_b32_e32 v43, v0
	v_mov_b32_e32 v44, v0
	v_mov_b32_e32 v45, v0
	v_mov_b32_e32 v46, v0
	v_mov_b32_e32 v47, v0
	v_mov_b32_e32 v48, v0
	v_mov_b32_e32 v49, v0
	v_mov_b32_e32 v50, v0
	v_mov_b32_e32 v51, v0
	v_mov_b32_e32 v52, v0
	v_mov_b32_e32 v53, v0
	v_mov_b32_e32 v54, v0
	v_mov_b32_e32 v55, v0
	v_mov_b32_e32 v56, v0
	v_mov_b32_e32 v57, v0
	v_mov_b32_e32 v58, v0
	v_mov_b32_e32 v59, v0
	v_mov_b32_e32 v60, v0
	v_mov_b32_e32 v61, v0
	v_mov_b32_e32 v62, v0
	v_mov_b32_e32 v63, v0
	s_waitcnt vmcnt(24)
	ds_write_b128 v138, v[64:67]
	ds_write_b128 v138, v[80:83] offset:16384
	ds_write_b128 v138, v[68:71] offset:4096
	ds_write_b128 v138, v[84:87] offset:20480
	ds_write_b128 v138, v[72:75] offset:8192
	ds_write_b128 v138, v[88:91] offset:24576
	ds_write_b128 v138, v[76:79] offset:12288
	ds_write_b128 v138, v[92:95] offset:28672
	s_waitcnt lgkmcnt(0)
	s_barrier
	global_load_dwordx4 v[64:67], v230, s[24:25] offset:512
	global_load_dwordx4 v[68:71], v230, s[30:31] offset:512
	global_load_dwordx4 v[72:75], v230, s[50:51] offset:512
	global_load_dwordx4 v[76:79], v230, s[54:55] offset:512
	global_load_dwordx4 v[80:83], v230, s[72:73] offset:512
	global_load_dwordx4 v[84:87], v230, s[74:75] offset:512
	global_load_dwordx4 v[88:91], v230, s[80:81] offset:512
	global_load_dwordx4 v[92:95], v230, s[86:87] offset:512
	ds_read_b128 v[142:145], v128
	ds_read_b128 v[146:149], v132 offset:16384
	ds_read_b128 v[150:153], v132 offset:20480
	s_waitcnt lgkmcnt(1)
	v_mfma_f32_32x32x16_bf16 v[48:63], v[142:145], v[146:149], v[48:63]
	s_waitcnt lgkmcnt(0)
	v_mfma_f32_32x32x16_bf16 v[32:47], v[142:145], v[150:153], v[32:47]
	ds_read_b128 v[142:145], v128 offset:4096
	s_waitcnt lgkmcnt(0)
	v_mfma_f32_32x32x16_bf16 v[16:31], v[142:145], v[146:149], v[16:31]
	ds_read_b128 v[146:149], v133 offset:16384
	v_mfma_f32_32x32x16_bf16 v[0:15], v[142:145], v[150:153], v[0:15]
	ds_read_b128 v[142:145], v129
	ds_read_b128 v[150:153], v133 offset:20480
	s_waitcnt lgkmcnt(1)
	v_mfma_f32_32x32x16_bf16 v[48:63], v[142:145], v[146:149], v[48:63]
	s_waitcnt lgkmcnt(0)
	v_mfma_f32_32x32x16_bf16 v[32:47], v[142:145], v[150:153], v[32:47]
	ds_read_b128 v[142:145], v129 offset:4096
	s_waitcnt lgkmcnt(0)
	v_mfma_f32_32x32x16_bf16 v[16:31], v[142:145], v[146:149], v[16:31]
	ds_read_b128 v[146:149], v228 offset:16384
	v_mfma_f32_32x32x16_bf16 v[0:15], v[142:145], v[150:153], v[0:15]
	ds_read_b128 v[142:145], v130
	ds_read_b128 v[150:153], v228 offset:20480
	s_waitcnt lgkmcnt(1)
	v_mfma_f32_32x32x16_bf16 v[48:63], v[142:145], v[146:149], v[48:63]
	s_waitcnt lgkmcnt(0)
	v_mfma_f32_32x32x16_bf16 v[32:47], v[142:145], v[150:153], v[32:47]
	ds_read_b128 v[142:145], v130 offset:4096
	s_waitcnt lgkmcnt(0)
	v_mfma_f32_32x32x16_bf16 v[16:31], v[142:145], v[146:149], v[16:31]
	ds_read_b128 v[146:149], v229 offset:16384
	v_mfma_f32_32x32x16_bf16 v[0:15], v[142:145], v[150:153], v[0:15]
	ds_read_b128 v[142:145], v131
	ds_read_b128 v[150:153], v229 offset:20480
	s_waitcnt lgkmcnt(1)
	v_mfma_f32_32x32x16_bf16 v[48:63], v[142:145], v[146:149], v[48:63]
	s_waitcnt lgkmcnt(0)
	v_mfma_f32_32x32x16_bf16 v[32:47], v[142:145], v[150:153], v[32:47]
	ds_read_b128 v[142:145], v131 offset:4096
	s_waitcnt lgkmcnt(0)
	v_mfma_f32_32x32x16_bf16 v[16:31], v[142:145], v[146:149], v[16:31]
	v_mfma_f32_32x32x16_bf16 v[0:15], v[142:145], v[150:153], v[0:15]
	s_waitcnt vmcnt(24)
	ds_write_b128 v138, v[96:99] offset:32768
	ds_write_b128 v138, v[112:115] offset:49152
	ds_write_b128 v138, v[100:103] offset:36864
	ds_write_b128 v138, v[116:119] offset:53248
	ds_write_b128 v138, v[104:107] offset:40960
	ds_write_b128 v138, v[120:123] offset:57344
	ds_write_b128 v138, v[108:111] offset:45056
	ds_write_b128 v138, v[124:127] offset:61440
	s_waitcnt lgkmcnt(0)
	s_barrier
	global_load_dwordx4 v[96:99], v230, s[24:25] offset:640
	global_load_dwordx4 v[100:103], v230, s[30:31] offset:640
	global_load_dwordx4 v[104:107], v230, s[50:51] offset:640
	global_load_dwordx4 v[108:111], v230, s[54:55] offset:640
	global_load_dwordx4 v[112:115], v230, s[72:73] offset:640
	global_load_dwordx4 v[116:119], v230, s[74:75] offset:640
	global_load_dwordx4 v[120:123], v230, s[80:81] offset:640
	global_load_dwordx4 v[124:127], v230, s[86:87] offset:640
	ds_read_b128 v[142:145], v128 offset:32768
	ds_read_b128 v[146:149], v132 offset:49152
	ds_read_b128 v[150:153], v132 offset:53248
	s_waitcnt lgkmcnt(1)
	v_mfma_f32_32x32x16_bf16 v[48:63], v[142:145], v[146:149], v[48:63]
	s_waitcnt lgkmcnt(0)
	v_mfma_f32_32x32x16_bf16 v[32:47], v[142:145], v[150:153], v[32:47]
	ds_read_b128 v[142:145], v128 offset:36864
	s_waitcnt lgkmcnt(0)
	v_mfma_f32_32x32x16_bf16 v[16:31], v[142:145], v[146:149], v[16:31]
	ds_read_b128 v[146:149], v133 offset:49152
	v_mfma_f32_32x32x16_bf16 v[0:15], v[142:145], v[150:153], v[0:15]
	ds_read_b128 v[142:145], v129 offset:32768
	ds_read_b128 v[150:153], v133 offset:53248
	s_waitcnt lgkmcnt(1)
	v_mfma_f32_32x32x16_bf16 v[48:63], v[142:145], v[146:149], v[48:63]
	s_waitcnt lgkmcnt(0)
	v_mfma_f32_32x32x16_bf16 v[32:47], v[142:145], v[150:153], v[32:47]
	ds_read_b128 v[142:145], v129 offset:36864
	s_waitcnt lgkmcnt(0)
	v_mfma_f32_32x32x16_bf16 v[16:31], v[142:145], v[146:149], v[16:31]
	ds_read_b128 v[146:149], v228 offset:49152
	v_mfma_f32_32x32x16_bf16 v[0:15], v[142:145], v[150:153], v[0:15]
	ds_read_b128 v[142:145], v130 offset:32768
	ds_read_b128 v[150:153], v228 offset:53248
	s_waitcnt lgkmcnt(1)
	v_mfma_f32_32x32x16_bf16 v[48:63], v[142:145], v[146:149], v[48:63]
	s_waitcnt lgkmcnt(0)
	v_mfma_f32_32x32x16_bf16 v[32:47], v[142:145], v[150:153], v[32:47]
	ds_read_b128 v[142:145], v130 offset:36864
	s_waitcnt lgkmcnt(0)
	v_mfma_f32_32x32x16_bf16 v[16:31], v[142:145], v[146:149], v[16:31]
	ds_read_b128 v[146:149], v229 offset:49152
	v_mfma_f32_32x32x16_bf16 v[0:15], v[142:145], v[150:153], v[0:15]
	ds_read_b128 v[142:145], v131 offset:32768
	ds_read_b128 v[150:153], v229 offset:53248
	s_waitcnt lgkmcnt(1)
	v_mfma_f32_32x32x16_bf16 v[48:63], v[142:145], v[146:149], v[48:63]
	s_waitcnt lgkmcnt(0)
	v_mfma_f32_32x32x16_bf16 v[32:47], v[142:145], v[150:153], v[32:47]
	ds_read_b128 v[142:145], v131 offset:36864
	s_waitcnt lgkmcnt(0)
	v_mfma_f32_32x32x16_bf16 v[16:31], v[142:145], v[146:149], v[16:31]
	v_mfma_f32_32x32x16_bf16 v[0:15], v[142:145], v[150:153], v[0:15]
	s_waitcnt vmcnt(24)
	ds_write_b128 v138, v[160:163]
	ds_write_b128 v138, v[176:179] offset:16384
	ds_write_b128 v138, v[164:167] offset:4096
	ds_write_b128 v138, v[180:183] offset:20480
	ds_write_b128 v138, v[168:171] offset:8192
	ds_write_b128 v138, v[184:187] offset:24576
	ds_write_b128 v138, v[172:175] offset:12288
	ds_write_b128 v138, v[188:191] offset:28672
	s_waitcnt lgkmcnt(0)
	s_barrier
	global_load_dwordx4 v[160:163], v230, s[24:25] offset:768
	global_load_dwordx4 v[164:167], v230, s[30:31] offset:768
	global_load_dwordx4 v[168:171], v230, s[50:51] offset:768
	global_load_dwordx4 v[172:175], v230, s[54:55] offset:768
	global_load_dwordx4 v[176:179], v230, s[72:73] offset:768
	global_load_dwordx4 v[180:183], v230, s[74:75] offset:768
	global_load_dwordx4 v[184:187], v230, s[80:81] offset:768
	global_load_dwordx4 v[188:191], v230, s[86:87] offset:768
	ds_read_b128 v[142:145], v128
	ds_read_b128 v[146:149], v132 offset:16384
	ds_read_b128 v[150:153], v132 offset:20480
	s_waitcnt lgkmcnt(1)
	v_mfma_f32_32x32x16_bf16 v[48:63], v[142:145], v[146:149], v[48:63]
	s_waitcnt lgkmcnt(0)
	v_mfma_f32_32x32x16_bf16 v[32:47], v[142:145], v[150:153], v[32:47]
	ds_read_b128 v[142:145], v128 offset:4096
	s_waitcnt lgkmcnt(0)
	v_mfma_f32_32x32x16_bf16 v[16:31], v[142:145], v[146:149], v[16:31]
	ds_read_b128 v[146:149], v133 offset:16384
	v_mfma_f32_32x32x16_bf16 v[0:15], v[142:145], v[150:153], v[0:15]
	ds_read_b128 v[142:145], v129
	ds_read_b128 v[150:153], v133 offset:20480
	s_waitcnt lgkmcnt(1)
	v_mfma_f32_32x32x16_bf16 v[48:63], v[142:145], v[146:149], v[48:63]
	s_waitcnt lgkmcnt(0)
	v_mfma_f32_32x32x16_bf16 v[32:47], v[142:145], v[150:153], v[32:47]
	ds_read_b128 v[142:145], v129 offset:4096
	s_waitcnt lgkmcnt(0)
	v_mfma_f32_32x32x16_bf16 v[16:31], v[142:145], v[146:149], v[16:31]
	ds_read_b128 v[146:149], v228 offset:16384
	v_mfma_f32_32x32x16_bf16 v[0:15], v[142:145], v[150:153], v[0:15]
	ds_read_b128 v[142:145], v130
	ds_read_b128 v[150:153], v228 offset:20480
	s_waitcnt lgkmcnt(1)
	v_mfma_f32_32x32x16_bf16 v[48:63], v[142:145], v[146:149], v[48:63]
	s_waitcnt lgkmcnt(0)
	v_mfma_f32_32x32x16_bf16 v[32:47], v[142:145], v[150:153], v[32:47]
	ds_read_b128 v[142:145], v130 offset:4096
	s_waitcnt lgkmcnt(0)
	v_mfma_f32_32x32x16_bf16 v[16:31], v[142:145], v[146:149], v[16:31]
	ds_read_b128 v[146:149], v229 offset:16384
	v_mfma_f32_32x32x16_bf16 v[0:15], v[142:145], v[150:153], v[0:15]
	ds_read_b128 v[142:145], v131
	ds_read_b128 v[150:153], v229 offset:20480
	s_waitcnt lgkmcnt(1)
	v_mfma_f32_32x32x16_bf16 v[48:63], v[142:145], v[146:149], v[48:63]
	s_waitcnt lgkmcnt(0)
	v_mfma_f32_32x32x16_bf16 v[32:47], v[142:145], v[150:153], v[32:47]
	ds_read_b128 v[142:145], v131 offset:4096
	s_waitcnt lgkmcnt(0)
	v_mfma_f32_32x32x16_bf16 v[16:31], v[142:145], v[146:149], v[16:31]
	v_mfma_f32_32x32x16_bf16 v[0:15], v[142:145], v[150:153], v[0:15]
	s_waitcnt vmcnt(24)
	ds_write_b128 v138, v[196:199] offset:32768
	ds_write_b128 v138, v[212:215] offset:49152
	ds_write_b128 v138, v[200:203] offset:36864
	ds_write_b128 v138, v[216:219] offset:53248
	ds_write_b128 v138, v[204:207] offset:40960
	ds_write_b128 v138, v[220:223] offset:57344
	ds_write_b128 v138, v[208:211] offset:45056
	ds_write_b128 v138, v[224:227] offset:61440
	s_waitcnt lgkmcnt(0)
	s_barrier
	global_load_dwordx4 v[196:199], v230, s[24:25] offset:896
	global_load_dwordx4 v[200:203], v230, s[30:31] offset:896
	global_load_dwordx4 v[204:207], v230, s[50:51] offset:896
	global_load_dwordx4 v[208:211], v230, s[54:55] offset:896
	global_load_dwordx4 v[212:215], v230, s[72:73] offset:896
	global_load_dwordx4 v[216:219], v230, s[74:75] offset:896
	global_load_dwordx4 v[220:223], v230, s[80:81] offset:896
	global_load_dwordx4 v[224:227], v230, s[86:87] offset:896
	ds_read_b128 v[142:145], v128 offset:32768
	ds_read_b128 v[146:149], v132 offset:49152
	ds_read_b128 v[150:153], v132 offset:53248
	s_waitcnt lgkmcnt(1)
	v_mfma_f32_32x32x16_bf16 v[48:63], v[142:145], v[146:149], v[48:63]
	s_waitcnt lgkmcnt(0)
	v_mfma_f32_32x32x16_bf16 v[32:47], v[142:145], v[150:153], v[32:47]
	ds_read_b128 v[142:145], v128 offset:36864
	s_waitcnt lgkmcnt(0)
	v_mfma_f32_32x32x16_bf16 v[16:31], v[142:145], v[146:149], v[16:31]
	ds_read_b128 v[146:149], v133 offset:49152
	v_mfma_f32_32x32x16_bf16 v[0:15], v[142:145], v[150:153], v[0:15]
	ds_read_b128 v[142:145], v129 offset:32768
	ds_read_b128 v[150:153], v133 offset:53248
	s_waitcnt lgkmcnt(1)
	v_mfma_f32_32x32x16_bf16 v[48:63], v[142:145], v[146:149], v[48:63]
	s_waitcnt lgkmcnt(0)
	v_mfma_f32_32x32x16_bf16 v[32:47], v[142:145], v[150:153], v[32:47]
	ds_read_b128 v[142:145], v129 offset:36864
	s_waitcnt lgkmcnt(0)
	v_mfma_f32_32x32x16_bf16 v[16:31], v[142:145], v[146:149], v[16:31]
	ds_read_b128 v[146:149], v228 offset:49152
	v_mfma_f32_32x32x16_bf16 v[0:15], v[142:145], v[150:153], v[0:15]
	ds_read_b128 v[142:145], v130 offset:32768
	ds_read_b128 v[150:153], v228 offset:53248
	s_waitcnt lgkmcnt(1)
	v_mfma_f32_32x32x16_bf16 v[48:63], v[142:145], v[146:149], v[48:63]
	s_waitcnt lgkmcnt(0)
	v_mfma_f32_32x32x16_bf16 v[32:47], v[142:145], v[150:153], v[32:47]
	ds_read_b128 v[142:145], v130 offset:36864
	s_waitcnt lgkmcnt(0)
	v_mfma_f32_32x32x16_bf16 v[16:31], v[142:145], v[146:149], v[16:31]
	ds_read_b128 v[146:149], v229 offset:49152
	v_mfma_f32_32x32x16_bf16 v[0:15], v[142:145], v[150:153], v[0:15]
	ds_read_b128 v[142:145], v131 offset:32768
	ds_read_b128 v[150:153], v229 offset:53248
	s_waitcnt lgkmcnt(1)
	v_mfma_f32_32x32x16_bf16 v[48:63], v[142:145], v[146:149], v[48:63]
	s_waitcnt lgkmcnt(0)
	v_mfma_f32_32x32x16_bf16 v[32:47], v[142:145], v[150:153], v[32:47]
	ds_read_b128 v[142:145], v131 offset:36864
	s_waitcnt lgkmcnt(0)
	v_mfma_f32_32x32x16_bf16 v[16:31], v[142:145], v[146:149], v[16:31]
	v_mfma_f32_32x32x16_bf16 v[0:15], v[142:145], v[150:153], v[0:15]
	s_waitcnt vmcnt(24)
	ds_write_b128 v138, v[64:67]
	ds_write_b128 v138, v[80:83] offset:16384
	ds_write_b128 v138, v[68:71] offset:4096
	ds_write_b128 v138, v[84:87] offset:20480
	ds_write_b128 v138, v[72:75] offset:8192
	ds_write_b128 v138, v[88:91] offset:24576
	ds_write_b128 v138, v[76:79] offset:12288
	ds_write_b128 v138, v[92:95] offset:28672
	s_waitcnt lgkmcnt(0)
	s_barrier
	ds_read_b128 v[142:145], v128
	ds_read_b128 v[146:149], v132 offset:16384
	ds_read_b128 v[150:153], v132 offset:20480
	s_waitcnt lgkmcnt(1)
	v_mfma_f32_32x32x16_bf16 v[48:63], v[142:145], v[146:149], v[48:63]
	s_waitcnt lgkmcnt(0)
	v_mfma_f32_32x32x16_bf16 v[32:47], v[142:145], v[150:153], v[32:47]
	ds_read_b128 v[142:145], v128 offset:4096
	s_waitcnt lgkmcnt(0)
	v_mfma_f32_32x32x16_bf16 v[16:31], v[142:145], v[146:149], v[16:31]
	ds_read_b128 v[146:149], v133 offset:16384
	v_mfma_f32_32x32x16_bf16 v[0:15], v[142:145], v[150:153], v[0:15]
	ds_read_b128 v[142:145], v129
	ds_read_b128 v[150:153], v133 offset:20480
	s_waitcnt lgkmcnt(1)
	v_mfma_f32_32x32x16_bf16 v[48:63], v[142:145], v[146:149], v[48:63]
	s_waitcnt lgkmcnt(0)
	v_mfma_f32_32x32x16_bf16 v[32:47], v[142:145], v[150:153], v[32:47]
	ds_read_b128 v[142:145], v129 offset:4096
	s_waitcnt lgkmcnt(0)
	v_mfma_f32_32x32x16_bf16 v[16:31], v[142:145], v[146:149], v[16:31]
	ds_read_b128 v[146:149], v228 offset:16384
	v_mfma_f32_32x32x16_bf16 v[0:15], v[142:145], v[150:153], v[0:15]
	ds_read_b128 v[142:145], v130
	ds_read_b128 v[150:153], v228 offset:20480
	s_waitcnt lgkmcnt(1)
	v_mfma_f32_32x32x16_bf16 v[48:63], v[142:145], v[146:149], v[48:63]
	s_waitcnt lgkmcnt(0)
	v_mfma_f32_32x32x16_bf16 v[32:47], v[142:145], v[150:153], v[32:47]
	ds_read_b128 v[142:145], v130 offset:4096
	s_waitcnt lgkmcnt(0)
	v_mfma_f32_32x32x16_bf16 v[16:31], v[142:145], v[146:149], v[16:31]
	ds_read_b128 v[146:149], v229 offset:16384
	v_mfma_f32_32x32x16_bf16 v[0:15], v[142:145], v[150:153], v[0:15]
	ds_read_b128 v[142:145], v131
	ds_read_b128 v[150:153], v229 offset:20480
	s_waitcnt lgkmcnt(1)
	v_mfma_f32_32x32x16_bf16 v[48:63], v[142:145], v[146:149], v[48:63]
	s_waitcnt lgkmcnt(0)
	v_mfma_f32_32x32x16_bf16 v[32:47], v[142:145], v[150:153], v[32:47]
	ds_read_b128 v[142:145], v131 offset:4096
	s_waitcnt lgkmcnt(0)
	v_mfma_f32_32x32x16_bf16 v[16:31], v[142:145], v[146:149], v[16:31]
	v_mfma_f32_32x32x16_bf16 v[0:15], v[142:145], v[150:153], v[0:15]
	s_waitcnt vmcnt(16)
	ds_write_b128 v138, v[96:99] offset:32768
	ds_write_b128 v138, v[112:115] offset:49152
	ds_write_b128 v138, v[100:103] offset:36864
	ds_write_b128 v138, v[116:119] offset:53248
	ds_write_b128 v138, v[104:107] offset:40960
	ds_write_b128 v138, v[120:123] offset:57344
	ds_write_b128 v138, v[108:111] offset:45056
	ds_write_b128 v138, v[124:127] offset:61440
	s_waitcnt lgkmcnt(0)
	s_barrier
	ds_read_b128 v[142:145], v128 offset:32768
	ds_read_b128 v[146:149], v132 offset:49152
	ds_read_b128 v[150:153], v132 offset:53248
	s_waitcnt lgkmcnt(1)
	v_mfma_f32_32x32x16_bf16 v[48:63], v[142:145], v[146:149], v[48:63]
	s_waitcnt lgkmcnt(0)
	v_mfma_f32_32x32x16_bf16 v[32:47], v[142:145], v[150:153], v[32:47]
	ds_read_b128 v[142:145], v128 offset:36864
	s_waitcnt lgkmcnt(0)
	v_mfma_f32_32x32x16_bf16 v[16:31], v[142:145], v[146:149], v[16:31]
	ds_read_b128 v[146:149], v133 offset:49152
	v_mfma_f32_32x32x16_bf16 v[0:15], v[142:145], v[150:153], v[0:15]
	ds_read_b128 v[142:145], v129 offset:32768
	ds_read_b128 v[150:153], v133 offset:53248
	s_waitcnt lgkmcnt(1)
	v_mfma_f32_32x32x16_bf16 v[48:63], v[142:145], v[146:149], v[48:63]
	s_waitcnt lgkmcnt(0)
	v_mfma_f32_32x32x16_bf16 v[32:47], v[142:145], v[150:153], v[32:47]
	ds_read_b128 v[142:145], v129 offset:36864
	s_waitcnt lgkmcnt(0)
	v_mfma_f32_32x32x16_bf16 v[16:31], v[142:145], v[146:149], v[16:31]
	ds_read_b128 v[146:149], v228 offset:49152
	v_mfma_f32_32x32x16_bf16 v[0:15], v[142:145], v[150:153], v[0:15]
	ds_read_b128 v[142:145], v130 offset:32768
	ds_read_b128 v[150:153], v228 offset:53248
	s_waitcnt lgkmcnt(1)
	v_mfma_f32_32x32x16_bf16 v[48:63], v[142:145], v[146:149], v[48:63]
	s_waitcnt lgkmcnt(0)
	v_mfma_f32_32x32x16_bf16 v[32:47], v[142:145], v[150:153], v[32:47]
	ds_read_b128 v[142:145], v130 offset:36864
	s_waitcnt lgkmcnt(0)
	v_mfma_f32_32x32x16_bf16 v[16:31], v[142:145], v[146:149], v[16:31]
	ds_read_b128 v[146:149], v229 offset:49152
	v_mfma_f32_32x32x16_bf16 v[0:15], v[142:145], v[150:153], v[0:15]
	ds_read_b128 v[142:145], v131 offset:32768
	ds_read_b128 v[150:153], v229 offset:53248
	s_waitcnt lgkmcnt(1)
	v_mfma_f32_32x32x16_bf16 v[48:63], v[142:145], v[146:149], v[48:63]
	s_waitcnt lgkmcnt(0)
	v_mfma_f32_32x32x16_bf16 v[32:47], v[142:145], v[150:153], v[32:47]
	ds_read_b128 v[142:145], v131 offset:36864
	s_waitcnt lgkmcnt(0)
	v_mfma_f32_32x32x16_bf16 v[16:31], v[142:145], v[146:149], v[16:31]
	v_mfma_f32_32x32x16_bf16 v[0:15], v[142:145], v[150:153], v[0:15]
	s_waitcnt vmcnt(8)
	ds_write_b128 v138, v[160:163]
	ds_write_b128 v138, v[176:179] offset:16384
	ds_write_b128 v138, v[164:167] offset:4096
	ds_write_b128 v138, v[180:183] offset:20480
	ds_write_b128 v138, v[168:171] offset:8192
	ds_write_b128 v138, v[184:187] offset:24576
	ds_write_b128 v138, v[172:175] offset:12288
	ds_write_b128 v138, v[188:191] offset:28672
	s_waitcnt lgkmcnt(0)
	s_barrier
	ds_read_b128 v[142:145], v128
	ds_read_b128 v[146:149], v132 offset:16384
	ds_read_b128 v[150:153], v132 offset:20480
	s_waitcnt lgkmcnt(1)
	v_mfma_f32_32x32x16_bf16 v[48:63], v[142:145], v[146:149], v[48:63]
	s_waitcnt lgkmcnt(0)
	v_mfma_f32_32x32x16_bf16 v[32:47], v[142:145], v[150:153], v[32:47]
	ds_read_b128 v[142:145], v128 offset:4096
	s_waitcnt lgkmcnt(0)
	v_mfma_f32_32x32x16_bf16 v[16:31], v[142:145], v[146:149], v[16:31]
	ds_read_b128 v[146:149], v133 offset:16384
	v_mfma_f32_32x32x16_bf16 v[0:15], v[142:145], v[150:153], v[0:15]
	ds_read_b128 v[142:145], v129
	ds_read_b128 v[150:153], v133 offset:20480
	s_waitcnt lgkmcnt(1)
	v_mfma_f32_32x32x16_bf16 v[48:63], v[142:145], v[146:149], v[48:63]
	s_waitcnt lgkmcnt(0)
	v_mfma_f32_32x32x16_bf16 v[32:47], v[142:145], v[150:153], v[32:47]
	ds_read_b128 v[142:145], v129 offset:4096
	s_waitcnt lgkmcnt(0)
	v_mfma_f32_32x32x16_bf16 v[16:31], v[142:145], v[146:149], v[16:31]
	ds_read_b128 v[146:149], v228 offset:16384
	v_mfma_f32_32x32x16_bf16 v[0:15], v[142:145], v[150:153], v[0:15]
	ds_read_b128 v[142:145], v130
	ds_read_b128 v[150:153], v228 offset:20480
	s_waitcnt lgkmcnt(1)
	v_mfma_f32_32x32x16_bf16 v[48:63], v[142:145], v[146:149], v[48:63]
	s_waitcnt lgkmcnt(0)
	v_mfma_f32_32x32x16_bf16 v[32:47], v[142:145], v[150:153], v[32:47]
	ds_read_b128 v[142:145], v130 offset:4096
	s_waitcnt lgkmcnt(0)
	v_mfma_f32_32x32x16_bf16 v[16:31], v[142:145], v[146:149], v[16:31]
	ds_read_b128 v[146:149], v229 offset:16384
	v_mfma_f32_32x32x16_bf16 v[0:15], v[142:145], v[150:153], v[0:15]
	ds_read_b128 v[142:145], v131
	ds_read_b128 v[150:153], v229 offset:20480
	s_waitcnt lgkmcnt(1)
	v_mfma_f32_32x32x16_bf16 v[48:63], v[142:145], v[146:149], v[48:63]
	s_waitcnt lgkmcnt(0)
	v_mfma_f32_32x32x16_bf16 v[32:47], v[142:145], v[150:153], v[32:47]
	ds_read_b128 v[142:145], v131 offset:4096
	s_waitcnt lgkmcnt(0)
	v_mfma_f32_32x32x16_bf16 v[16:31], v[142:145], v[146:149], v[16:31]
	v_mfma_f32_32x32x16_bf16 v[0:15], v[142:145], v[150:153], v[0:15]
	s_waitcnt vmcnt(0)
	ds_write_b128 v138, v[196:199] offset:32768
	ds_write_b128 v138, v[212:215] offset:49152
	ds_write_b128 v138, v[200:203] offset:36864
	ds_write_b128 v138, v[216:219] offset:53248
	ds_write_b128 v138, v[204:207] offset:40960
	ds_write_b128 v138, v[220:223] offset:57344
	ds_write_b128 v138, v[208:211] offset:45056
	ds_write_b128 v138, v[224:227] offset:61440
	s_waitcnt lgkmcnt(0)
	s_barrier
	ds_read_b128 v[142:145], v128 offset:32768
	ds_read_b128 v[146:149], v132 offset:49152
	ds_read_b128 v[150:153], v132 offset:53248
	s_waitcnt lgkmcnt(1)
	v_mfma_f32_32x32x16_bf16 v[48:63], v[142:145], v[146:149], v[48:63]
	s_waitcnt lgkmcnt(0)
	v_mfma_f32_32x32x16_bf16 v[32:47], v[142:145], v[150:153], v[32:47]
	ds_read_b128 v[142:145], v128 offset:36864
	s_waitcnt lgkmcnt(0)
	v_mfma_f32_32x32x16_bf16 v[16:31], v[142:145], v[146:149], v[16:31]
	ds_read_b128 v[146:149], v133 offset:49152
	v_mfma_f32_32x32x16_bf16 v[0:15], v[142:145], v[150:153], v[0:15]
	ds_read_b128 v[142:145], v129 offset:32768
	ds_read_b128 v[150:153], v133 offset:53248
	s_waitcnt lgkmcnt(1)
	v_mfma_f32_32x32x16_bf16 v[48:63], v[142:145], v[146:149], v[48:63]
	s_waitcnt lgkmcnt(0)
	v_mfma_f32_32x32x16_bf16 v[32:47], v[142:145], v[150:153], v[32:47]
	ds_read_b128 v[142:145], v129 offset:36864
	s_waitcnt lgkmcnt(0)
	v_mfma_f32_32x32x16_bf16 v[16:31], v[142:145], v[146:149], v[16:31]
	ds_read_b128 v[146:149], v228 offset:49152
	v_mfma_f32_32x32x16_bf16 v[0:15], v[142:145], v[150:153], v[0:15]
	ds_read_b128 v[142:145], v130 offset:32768
	ds_read_b128 v[150:153], v228 offset:53248
	s_waitcnt lgkmcnt(1)
	v_mfma_f32_32x32x16_bf16 v[48:63], v[142:145], v[146:149], v[48:63]
	s_waitcnt lgkmcnt(0)
	v_mfma_f32_32x32x16_bf16 v[32:47], v[142:145], v[150:153], v[32:47]
	ds_read_b128 v[142:145], v130 offset:36864
	s_waitcnt lgkmcnt(0)
	v_mfma_f32_32x32x16_bf16 v[16:31], v[142:145], v[146:149], v[16:31]
	ds_read_b128 v[146:149], v229 offset:49152
	v_mfma_f32_32x32x16_bf16 v[0:15], v[142:145], v[150:153], v[0:15]
	ds_read_b128 v[142:145], v131 offset:32768
	ds_read_b128 v[150:153], v229 offset:53248
	s_waitcnt lgkmcnt(1)
	v_mfma_f32_32x32x16_bf16 v[48:63], v[142:145], v[146:149], v[48:63]
	s_waitcnt lgkmcnt(0)
	v_mfma_f32_32x32x16_bf16 v[32:47], v[142:145], v[150:153], v[32:47]
	ds_read_b128 v[142:145], v131 offset:36864
	s_waitcnt lgkmcnt(0)
	v_mfma_f32_32x32x16_bf16 v[16:31], v[142:145], v[146:149], v[16:31]
	v_mfma_f32_32x32x16_bf16 v[0:15], v[142:145], v[150:153], v[0:15]
	s_barrier
	s_waitcnt vmcnt(7)
	v_mov_b32_e32 v64, v235
	s_mov_b32 s1, 0x7fffc0
	v_lshrrev_b32_e32 v66, 3, v64
	v_lshrrev_b32_e32 v65, 1, v64
	v_and_b32_e32 v66, 4, v66
	v_and_or_b32 v65, v65, s1, v66
	v_and_b32_e32 v64, 0x5f, v64
	v_lshlrev_b32_e32 v65, 9, v65
	v_lshlrev_b32_e32 v64, 2, v64
	v_add3_u32 v64, s36, v65, v64
	ds_write2_b32 v64, v48, v32 offset1:32
	ds_write2_b32 v64, v49, v33 offset0:128 offset1:160
	v_add_u32_e32 v32, 0x400, v64
	ds_write2_b32 v32, v50, v34 offset1:32
	ds_write2_b32 v32, v51, v35 offset0:128 offset1:160
	v_add_u32_e32 v32, 0x1000, v64
	ds_write2_b32 v32, v52, v36 offset1:32
	ds_write2_b32 v32, v53, v37 offset0:128 offset1:160
	v_add_u32_e32 v32, 0x1400, v64
	ds_write2_b32 v32, v54, v38 offset1:32
	ds_write2_b32 v32, v55, v39 offset0:128 offset1:160
	v_add_u32_e32 v32, 0x2000, v64
	ds_write2_b32 v32, v56, v40 offset1:32
	ds_write2_b32 v32, v57, v41 offset0:128 offset1:160
	v_add_u32_e32 v32, 0x2400, v64
	ds_write2_b32 v32, v58, v42 offset1:32
	ds_write2_b32 v32, v59, v43 offset0:128 offset1:160
	v_add_u32_e32 v32, 0x3000, v64
	ds_write2_b32 v32, v60, v44 offset1:32
	ds_write2_b32 v32, v61, v45 offset0:128 offset1:160
	v_add_u32_e32 v32, 0x3400, v64
	ds_write2_b32 v32, v62, v46 offset1:32
	ds_write2_b32 v32, v63, v47 offset0:128 offset1:160
	v_add_u32_e32 v32, 0x4000, v64
	ds_write2_b32 v32, v16, v0 offset1:32
	ds_write2_b32 v32, v17, v1 offset0:128 offset1:160
	v_add_u32_e32 v0, 0x4400, v64
	ds_write2_b32 v0, v18, v2 offset1:32
	ds_write2_b32 v0, v19, v3 offset0:128 offset1:160
	v_add_u32_e32 v0, 0x5000, v64
	ds_write2_b32 v0, v20, v4 offset1:32
	ds_write2_b32 v0, v21, v5 offset0:128 offset1:160
	v_add_u32_e32 v0, 0x5400, v64
	ds_write2_b32 v0, v22, v6 offset1:32
	ds_write2_b32 v0, v23, v7 offset0:128 offset1:160
	v_add_u32_e32 v0, 0x6000, v64
	ds_write2_b32 v0, v24, v8 offset1:32
	ds_write2_b32 v0, v25, v9 offset0:128 offset1:160
	v_add_u32_e32 v0, 0x6400, v64
	s_lshl_b32 s1, s40, 7
	v_readlane_b32 s8, v255, 37
	s_mul_hi_u32 s10, s40, 0x15555556
	s_and_b32 s0, 0xffff, s41
	ds_write2_b32 v0, v26, v10 offset1:32
	ds_write2_b32 v0, v27, v11 offset0:128 offset1:160
	v_add_u32_e32 v0, 0x7000, v64
	s_add_i32 s1, s8, s1
	s_mulk_i32 s10, 0x600
	s_lshl_b32 s0, s0, 7
	ds_write2_b32 v0, v28, v12 offset1:32
	ds_write2_b32 v0, v29, v13 offset0:128 offset1:160
	v_add_u32_e32 v0, 0x7400, v64
	s_sub_i32 s1, s1, s10
	s_mov_b32 s10, 0
	ds_write2_b32 v0, v30, v14 offset1:32
	ds_write2_b32 v0, v31, v15 offset0:128 offset1:160
	v_lshlrev_b32_e32 v232, 3, v235
	v_and_b32_e32 v232, 0x78, v232
	v_or_b32_e32 v232, s0, v232
	v_ashrrev_i32_e32 v233, 4, v235
	v_add_u32_e32 v233, s1, v233
	v_mov_b64_e32 v[224:225], s[58:59]
	v_mad_i64_i32 v[224:225], s[46:47], v233, s94, v[224:225]
	v_ashrrev_i32_e32 v227, 31, v233
	v_mov_b32_e32 v226, v233
	v_lshlrev_b64 v[226:227], 10, v[226:227]
	v_lshl_add_u64 v[226:227], s[60:61], 0, v[226:227]
	v_lshlrev_b32_e32 v233, 1, v232
	v_mov_b32_e32 v229, 0
	v_mov_b32_e32 v228, v233
	v_lshl_add_u64 v[224:225], v[224:225], 0, v[228:229]
	v_lshl_add_u64 v[226:227], v[226:227], 0, v[228:229]
	v_lshlrev_b32_e32 v232, 2, v232
	global_load_dwordx4 v[212:215], v232, s[12:13]
	global_load_dwordx4 v[228:231], v232, s[12:13] offset:16
	global_load_dwordx4 v[216:219], v[224:225], off
	global_load_dwordx4 v[220:223], v[226:227], off
	s_mov_b32 s46, 0x20200
	s_mov_b32 s47, 0
	s_mov_b32 s48, 0x4000
	s_mov_b32 s49, 0
	s_waitcnt lgkmcnt(0)
	s_barrier
	s_waitcnt vmcnt(0)
.LBB0_767:
	s_nop 0
	v_mov_b32_e32 v2, v235
	v_mov_b32_e32 v3, v235
	s_add_i32 s40, s1, s10
	v_ashrrev_i32_e32 v2, 4, v2
	v_lshlrev_b32_e32 v3, 3, v3
	v_and_b32_e32 v3, 0x78, v3
	v_add_lshl_u32 v4, s10, v2, 9
	v_add_u32_e32 v2, s40, v2
	v_mov_b64_e32 v[0:1], s[58:59]
	v_lshlrev_b32_e32 v5, 2, v3
	v_or_b32_e32 v6, s0, v3
	v_ashrrev_i32_e32 v3, 31, v2
	v_mad_i64_i32 v[16:17], s[40:41], v2, s94, v[0:1]
	v_lshlrev_b64 v[18:19], 10, v[2:3]
	v_lshlrev_b32_e32 v192, 1, v6
	v_add3_u32 v12, s36, v5, v4
	v_lshlrev_b32_e32 v4, 2, v6
	v_lshl_add_u64 v[20:21], s[60:61], 0, v[18:19]
	v_lshl_add_u64 v[16:17], v[16:17], 0, v[192:193]
	ds_read_b128 v[8:11], v12
	ds_read_b128 v[12:15], v12 offset:16
	v_lshl_add_u64 v[22:23], s[62:63], 0, v[18:19]
	v_lshl_add_u64 v[20:21], v[20:21], 0, v[192:193]
	v_lshl_add_u64 v[24:25], v[22:23], 0, v[192:193]
	s_add_i32 s10, s10, 16
	s_cmpk_eq_i32 s10, 0x80
	s_waitcnt lgkmcnt(1)
	v_add_f32_e32 v8, v8, v212
	v_add_f32_e32 v9, v9, v213
	v_add_f32_e32 v10, v10, v214
	v_add_f32_e32 v11, v11, v215
	s_waitcnt lgkmcnt(0)
	v_add_f32_e32 v12, v12, v228
	v_add_f32_e32 v13, v13, v229
	v_add_f32_e32 v14, v14, v230
	v_add_f32_e32 v15, v15, v231
	s_waitcnt vmcnt(1)
	v_lshlrev_b32_e32 v0, 16, v216
	v_and_b32_e32 v1, 0xffff0000, v216
	v_lshlrev_b32_e32 v2, 16, v217
	v_and_b32_e32 v3, 0xffff0000, v217
	v_lshlrev_b32_e32 v4, 16, v218
	v_and_b32_e32 v5, 0xffff0000, v218
	v_lshlrev_b32_e32 v6, 16, v219
	v_and_b32_e32 v7, 0xffff0000, v219
	v_mul_f32_e32 v16, 0xbfb8aa3b, v8
	v_mul_f32_e32 v17, 0xbfb8aa3b, v9
	v_mul_f32_e32 v18, 0xbfb8aa3b, v10
	v_mul_f32_e32 v19, 0xbfb8aa3b, v11
	v_mul_f32_e32 v26, 0xbfb8aa3b, v12
	v_mul_f32_e32 v27, 0xbfb8aa3b, v13
	v_mul_f32_e32 v28, 0xbfb8aa3b, v14
	v_mul_f32_e32 v29, 0xbfb8aa3b, v15
	v_lshlrev_b32_e32 v8, 16, v220
	v_and_b32_e32 v9, 0xffff0000, v220
	v_lshlrev_b32_e32 v10, 16, v221
	v_and_b32_e32 v11, 0xffff0000, v221
	v_lshlrev_b32_e32 v12, 16, v222
	v_and_b32_e32 v13, 0xffff0000, v222
	v_lshlrev_b32_e32 v14, 16, v223
	v_and_b32_e32 v15, 0xffff0000, v223
	s_cbranch_scc1 .Lglu_nopf
	v_lshl_add_u64 v[224:225], s[46:47], 0, v[224:225]
	v_lshl_add_u64 v[226:227], s[48:49], 0, v[226:227]
	global_load_dwordx4 v[216:219], v[224:225], off
	global_load_dwordx4 v[220:223], v[226:227], off
.Lglu_nopf:
	v_mul_f32_e32 v20, 0xbfb8aa3b, v0
	v_mul_f32_e32 v21, 0xbfb8aa3b, v1
	v_mul_f32_e32 v22, 0xbfb8aa3b, v2
	v_mul_f32_e32 v23, 0xbfb8aa3b, v3
	v_mul_f32_e32 v30, 0xbfb8aa3b, v4
	v_mul_f32_e32 v31, 0xbfb8aa3b, v5
	v_mul_f32_e32 v32, 0xbfb8aa3b, v6
	v_mul_f32_e32 v33, 0xbfb8aa3b, v7
	v_exp_f32_e32 v16, v16
	v_exp_f32_e32 v17, v17
	v_exp_f32_e32 v18, v18
	v_exp_f32_e32 v19, v19
	v_exp_f32_e32 v26, v26
	v_exp_f32_e32 v27, v27
	v_exp_f32_e32 v28, v28
	v_exp_f32_e32 v29, v29
	v_exp_f32_e32 v20, v20
	v_exp_f32_e32 v21, v21
	v_exp_f32_e32 v22, v22
	v_exp_f32_e32 v23, v23
	v_exp_f32_e32 v30, v30
	v_exp_f32_e32 v31, v31
	v_exp_f32_e32 v32, v32
	v_exp_f32_e32 v33, v33
	v_add_f32_e32 v16, 1.0, v16
	v_add_f32_e32 v17, 1.0, v17
	v_add_f32_e32 v18, 1.0, v18
	v_add_f32_e32 v19, 1.0, v19
	v_add_f32_e32 v26, 1.0, v26
	v_add_f32_e32 v27, 1.0, v27
	v_add_f32_e32 v28, 1.0, v28
	v_add_f32_e32 v29, 1.0, v29
	v_add_f32_e32 v34, 1.0, v20
	v_add_f32_e32 v35, 1.0, v21
	v_add_f32_e32 v36, 1.0, v22
	v_add_f32_e32 v37, 1.0, v23
	v_add_f32_e32 v30, 1.0, v30
	v_add_f32_e32 v31, 1.0, v31
	v_add_f32_e32 v32, 1.0, v32
	v_add_f32_e32 v33, 1.0, v33
	v_rcp_f32_e32 v16, v16
	v_rcp_f32_e32 v17, v17
	v_rcp_f32_e32 v18, v18
	v_rcp_f32_e32 v19, v19
	v_rcp_f32_e32 v20, v26
	v_rcp_f32_e32 v21, v27
	v_rcp_f32_e32 v22, v28
	v_rcp_f32_e32 v23, v29
	v_rcp_f32_e32 v26, v34
	v_rcp_f32_e32 v27, v35
	v_rcp_f32_e32 v28, v36
	v_rcp_f32_e32 v29, v37
	v_rcp_f32_e32 v30, v30
	v_rcp_f32_e32 v31, v31
	v_rcp_f32_e32 v32, v32
	v_rcp_f32_e32 v33, v33
	v_pk_mul_f32 v[8:9], v[16:17], v[8:9]
	v_pk_mul_f32 v[10:11], v[18:19], v[10:11]
	v_pk_mul_f32 v[12:13], v[20:21], v[12:13]
	v_pk_mul_f32 v[14:15], v[22:23], v[14:15]
	v_pk_mul_f32 v[0:1], v[26:27], v[0:1]
	v_pk_mul_f32 v[2:3], v[28:29], v[2:3]
	v_pk_mul_f32 v[4:5], v[30:31], v[4:5]
	v_pk_mul_f32 v[6:7], v[32:33], v[6:7]
	v_pk_mul_f32 v[0:1], v[0:1], v[8:9]
	v_pk_mul_f32 v[2:3], v[2:3], v[10:11]
	v_pk_mul_f32 v[4:5], v[4:5], v[12:13]
	v_pk_mul_f32 v[6:7], v[6:7], v[14:15]
	v_cvt_pk_bf16_f32 v0, v0, v1
	v_cvt_pk_bf16_f32 v1, v2, v3
	v_cvt_pk_bf16_f32 v2, v4, v5
	v_cvt_pk_bf16_f32 v3, v6, v7
	global_store_dwordx4 v[24:25], v[0:3], off
	s_cbranch_scc0 .LBB0_767
	s_add_i32 s39, s39, 1
	s_mov_b64 s[0:1], 0
	s_barrier
	s_branch .LBB0_762
